# DOWN GEMM: hand-written residual epilogue; layer-0 leftover tiles (136 tiles over 64 blocks per XCD) split into two 128-row half tiles run by two blocks with half the MFMAs/A loads per k-step
# speedup vs baseline: 1.0027x; 1.0027x over previous
.LBB0_1084:
	s_or_b64 exec, exec, s[0:1]
	v_readlane_b32 s5, v253, 0
	s_waitcnt lgkmcnt(0)
	s_barrier
	s_ashr_i32 s2, s5, 3
	s_cmp_ge_i32 s2, s26
	s_cbranch_scc1 .LBB0_1089
	v_readlane_b32 s0, v254, 45
	v_readlane_b32 s1, v254, 46
	s_add_u32 s0, s0, 0x5000
	v_readlane_b32 s6, v254, 41
	s_addc_u32 s1, s1, 0
	s_mul_i32 s3, s6, 0x580000
	s_add_u32 s3, s54, s3
	s_addc_u32 s4, s55, 0
	s_and_b32 s5, s5, 7
	s_mul_i32 s5, s5, s25
	v_readlane_b32 s7, v254, 42
	s_mov_b32 s100, 0
.LBB0_1086:
	s_ashr_i32 s6, s2, 31
	s_lshr_b32 s6, s6, 26
	s_add_i32 s6, s2, s6
	s_ashr_i32 s7, s6, 6
	s_lshl_b32 s7, s7, 3
	s_sub_i32 s8, s25, s7
	s_min_i32 s8, s8, 8
	s_abs_i32 s9, s8
	v_cvt_f32_u32_e32 v0, s9
	s_sub_i32 s12, 0, s9
	s_andn2_b32 s6, s6, 63
	s_sub_i32 s10, s2, s6
	v_rcp_iflag_f32_e32 v0, v0
	s_abs_i32 s6, s10
	s_xor_b32 s11, s10, s8
	s_ashr_i32 s11, s11, 31
	v_mul_f32_e32 v0, 0x4f7ffffe, v0
	v_cvt_u32_f32_e32 v0, v0
	v_mov_b32_e32 v181, v179
	v_readfirstlane_b32 s13, v0
	s_mul_i32 s12, s12, s13
	s_mul_hi_u32 s12, s13, s12
	s_add_i32 s13, s13, s12
	s_mul_hi_u32 s12, s6, s13
	s_mul_i32 s13, s12, s9
	s_sub_i32 s6, s6, s13
	s_add_i32 s14, s12, 1
	s_sub_i32 s13, s6, s9
	s_cmp_ge_u32 s6, s9
	s_cselect_b32 s12, s14, s12
	s_cselect_b32 s6, s13, s6
	s_add_i32 s13, s12, 1
	s_cmp_ge_u32 s6, s9
	s_cselect_b32 s6, s13, s12
	s_xor_b32 s6, s6, s11
	s_sub_i32 s6, s6, s11
	s_mul_i32 s8, s8, s6
	s_add_i32 s7, s7, s5
	s_sub_i32 s8, s10, s8
	v_ashrrev_i32_e32 v237, 6, v181
	s_add_i32 s7, s7, s8
	v_lshlrev_b32_e32 v0, 1, v237
	v_bfe_u32 v183, v181, 5, 1
	v_lshl_add_u32 v2, s7, 3, v0
	v_mov_b64_e32 v[0:1], s[66:67]
	v_and_b32_e32 v238, 31, v181
	v_mad_i64_i32 v[0:1], s[8:9], v2, s24, v[0:1]
	v_lshlrev_b32_e32 v176, 9, v183
	v_lshl_add_u64 v[0:1], v[0:1], 0, v[176:177]
	v_lshlrev_b32_e32 v176, 4, v238
	v_ashrrev_i32_e32 v38, 2, v181
	s_mul_i32 s8, s6, 0xb0000
	v_lshl_add_u64 v[184:185], v[0:1], 0, v[176:177]
	s_mul_hi_i32 s9, s6, 0xb0000
	s_add_u32 s8, s3, s8
	v_lshlrev_b32_e32 v0, 5, v38
	s_addc_u32 s9, s4, s9
	v_ashrrev_i32_e32 v1, 31, v0
	v_lshlrev_b32_e32 v2, 4, v181
	v_lshl_add_u64 v[0:1], v[0:1], 1, s[8:9]
	v_and_b32_e32 v176, 48, v2
	v_lshl_add_u64 v[186:187], v[0:1], 0, v[176:177]
	s_movk_i32 s8, 0x2000
	v_add_co_u32_e32 v34, vcc, s8, v186
	v_mul_u32_u24_e32 v36, 40, v238
	s_nop 0
	v_addc_co_u32_e32 v35, vcc, 0, v187, vcc
	v_lshlrev_b32_e32 v37, 4, v183
	v_lshl_add_u32 v240, v36, 1, v37
	v_add_co_u32_e32 v36, vcc, s24, v184
	s_movk_i32 s9, 0x50
	s_nop 0
	v_addc_co_u32_e32 v37, vcc, 0, v185, vcc
	v_and_b32_e32 v239, 63, v181
	s_cmp_eq_u32 s100, 1
	s_cbranch_scc1 .Lhx_down_half
	v_bfe_u32 v247, v181, 4, 2
	v_lshlrev_b32_e32 v247, 1, v247
	v_mov_b32_e32 v176, 0x78
	v_lshrrev_b32_e32 v247, v247, v176
	v_and_b32_e32 v247, 3, v247
	v_and_b32_e32 v246, 3, v181
	v_xor_b32_e32 v247, v247, v246
	v_lshlrev_b32_e32 v247, 4, v247
	v_and_b32_e32 v188, 0xffffffcf, v186
	v_or_b32_e32 v188, v188, v247
	v_mov_b32_e32 v189, v187
	v_lshrrev_b32_e32 v176, 6, v181
	v_lshlrev_b32_e32 v247, 11, v176
	v_lshlrev_b32_e32 v176, 10, v176
	v_lshl_add_u64 v[188:189], v[188:189], 0, v[176:177]
	v_readfirstlane_b32 vcc_lo, v247
	v_bfe_u32 v247, v181, 4, 1
	v_lshlrev_b32_e32 v176, 9, v183
	v_lshl_add_u32 v176, v247, 8, v176
	v_lshl_add_u64 v[184:185], v[184:185], 0, v[176:177]
	v_mov_b32_e32 v176, s24
	v_lshl_add_u64 v[186:187], v[184:185], 0, v[176:177]
	v_mov_b32_e32 v176, 0x78
	v_bfe_u32 v247, v181, 2, 2
	v_lshlrev_b32_e32 v247, 1, v247
	v_lshrrev_b32_e32 v247, v247, v176
	v_and_b32_e32 v247, 3, v247
	v_bfe_u32 v246, v181, 4, 2
	v_xor_b32_e32 v247, v247, v246
	v_lshlrev_b32_e32 v247, 4, v247
	v_and_b32_e32 v246, 15, v181
	v_lshl_add_u32 v246, v246, 6, v247
	s_mov_b32 s96, 0
	s_mov_b32 m0, vcc_lo
	v_lshl_add_u64 v[160:161], v[188:189], 0, s[96:97]
	global_load_lds_dwordx4 v[160:161], off
	global_load_lds_dwordx4 v[160:161], off offset:1024
	s_mov_b32 s96, 0
	v_lshl_add_u64 v[248:249], v[184:185], 0, s[96:97]
	v_lshl_add_u64 v[250:251], v[186:187], 0, s[96:97]
	global_load_dwordx4 v[128:131], v[248:249], off
	global_load_dwordx4 v[132:135], v[248:249], off offset:256
	global_load_dwordx4 v[136:139], v[250:251], off
	global_load_dwordx4 v[140:143], v[250:251], off offset:256
	s_movk_i32 s96, 0x2000
	s_add_i32 m0, vcc_lo, 8192
	v_lshl_add_u64 v[160:161], v[188:189], 0, s[96:97]
	global_load_lds_dwordx4 v[160:161], off
	global_load_lds_dwordx4 v[160:161], off offset:1024
	s_movk_i32 s96, 0x800
	v_lshl_add_u64 v[248:249], v[184:185], 0, s[96:97]
	v_lshl_add_u64 v[250:251], v[186:187], 0, s[96:97]
	global_load_dwordx4 v[144:147], v[248:249], off
	global_load_dwordx4 v[148:151], v[248:249], off offset:256
	global_load_dwordx4 v[152:155], v[250:251], off
	global_load_dwordx4 v[156:159], v[250:251], off offset:256
	v_mov_b32_e32 v0, 0
	v_mov_b32_e32 v1, 0
	v_mov_b32_e32 v2, 0
	v_mov_b32_e32 v3, 0
	v_mov_b32_e32 v4, 0
	v_mov_b32_e32 v5, 0
	v_mov_b32_e32 v6, 0
	v_mov_b32_e32 v7, 0
	v_mov_b32_e32 v8, 0
	v_mov_b32_e32 v9, 0
	v_mov_b32_e32 v10, 0
	v_mov_b32_e32 v11, 0
	v_mov_b32_e32 v12, 0
	v_mov_b32_e32 v13, 0
	v_mov_b32_e32 v14, 0
	v_mov_b32_e32 v15, 0
	v_mov_b32_e32 v16, 0
	v_mov_b32_e32 v17, 0
	v_mov_b32_e32 v18, 0
	v_mov_b32_e32 v19, 0
	v_mov_b32_e32 v20, 0
	v_mov_b32_e32 v21, 0
	v_mov_b32_e32 v22, 0
	v_mov_b32_e32 v23, 0
	v_mov_b32_e32 v24, 0
	v_mov_b32_e32 v25, 0
	v_mov_b32_e32 v26, 0
	v_mov_b32_e32 v27, 0
	v_mov_b32_e32 v28, 0
	v_mov_b32_e32 v29, 0
	v_mov_b32_e32 v30, 0
	v_mov_b32_e32 v31, 0
	v_mov_b32_e32 v32, 0
	v_mov_b32_e32 v33, 0
	v_mov_b32_e32 v34, 0
	v_mov_b32_e32 v35, 0
	v_mov_b32_e32 v36, 0
	v_mov_b32_e32 v37, 0
	v_mov_b32_e32 v38, 0
	v_mov_b32_e32 v39, 0
	v_mov_b32_e32 v40, 0
	v_mov_b32_e32 v41, 0
	v_mov_b32_e32 v42, 0
	v_mov_b32_e32 v43, 0
	v_mov_b32_e32 v44, 0
	v_mov_b32_e32 v45, 0
	v_mov_b32_e32 v46, 0
	v_mov_b32_e32 v47, 0
	v_mov_b32_e32 v48, 0
	v_mov_b32_e32 v49, 0
	v_mov_b32_e32 v50, 0
	v_mov_b32_e32 v51, 0
	v_mov_b32_e32 v52, 0
	v_mov_b32_e32 v53, 0
	v_mov_b32_e32 v54, 0
	v_mov_b32_e32 v55, 0
	v_mov_b32_e32 v56, 0
	v_mov_b32_e32 v57, 0
	v_mov_b32_e32 v58, 0
	v_mov_b32_e32 v59, 0
	v_mov_b32_e32 v60, 0
	v_mov_b32_e32 v61, 0
	v_mov_b32_e32 v62, 0
	v_mov_b32_e32 v63, 0
	v_mov_b32_e32 v64, 0
	v_mov_b32_e32 v65, 0
	v_mov_b32_e32 v66, 0
	v_mov_b32_e32 v67, 0
	v_mov_b32_e32 v68, 0
	v_mov_b32_e32 v69, 0
	v_mov_b32_e32 v70, 0
	v_mov_b32_e32 v71, 0
	v_mov_b32_e32 v72, 0
	v_mov_b32_e32 v73, 0
	v_mov_b32_e32 v74, 0
	v_mov_b32_e32 v75, 0
	v_mov_b32_e32 v76, 0
	v_mov_b32_e32 v77, 0
	v_mov_b32_e32 v78, 0
	v_mov_b32_e32 v79, 0
	v_mov_b32_e32 v80, 0
	v_mov_b32_e32 v81, 0
	v_mov_b32_e32 v82, 0
	v_mov_b32_e32 v83, 0
	v_mov_b32_e32 v84, 0
	v_mov_b32_e32 v85, 0
	v_mov_b32_e32 v86, 0
	v_mov_b32_e32 v87, 0
	v_mov_b32_e32 v88, 0
	v_mov_b32_e32 v89, 0
	v_mov_b32_e32 v90, 0
	v_mov_b32_e32 v91, 0
	v_mov_b32_e32 v92, 0
	v_mov_b32_e32 v93, 0
	v_mov_b32_e32 v94, 0
	v_mov_b32_e32 v95, 0
	v_mov_b32_e32 v96, 0
	v_mov_b32_e32 v97, 0
	v_mov_b32_e32 v98, 0
	v_mov_b32_e32 v99, 0
	v_mov_b32_e32 v100, 0
	v_mov_b32_e32 v101, 0
	v_mov_b32_e32 v102, 0
	v_mov_b32_e32 v103, 0
	v_mov_b32_e32 v104, 0
	v_mov_b32_e32 v105, 0
	v_mov_b32_e32 v106, 0
	v_mov_b32_e32 v107, 0
	v_mov_b32_e32 v108, 0
	v_mov_b32_e32 v109, 0
	v_mov_b32_e32 v110, 0
	v_mov_b32_e32 v111, 0
	v_mov_b32_e32 v112, 0
	v_mov_b32_e32 v113, 0
	v_mov_b32_e32 v114, 0
	v_mov_b32_e32 v115, 0
	v_mov_b32_e32 v116, 0
	v_mov_b32_e32 v117, 0
	v_mov_b32_e32 v118, 0
	v_mov_b32_e32 v119, 0
	v_mov_b32_e32 v120, 0
	v_mov_b32_e32 v121, 0
	v_mov_b32_e32 v122, 0
	v_mov_b32_e32 v123, 0
	v_mov_b32_e32 v124, 0
	v_mov_b32_e32 v125, 0
	v_mov_b32_e32 v126, 0
	v_mov_b32_e32 v127, 0
	s_mov_b32 s8, 0
	s_waitcnt vmcnt(4)
	s_barrier
.Lg16_down_k:
	s_add_i32 s9, s8, 2
	s_lshl_b32 s96, s9, 13
	s_add_i32 m0, vcc_lo, 16384
	v_lshl_add_u64 v[160:161], v[188:189], 0, s[96:97]
	global_load_lds_dwordx4 v[160:161], off
	global_load_lds_dwordx4 v[160:161], off offset:1024
	ds_read_b128 v[196:199], v246 offset:0
	ds_read_b128 v[200:203], v246 offset:1024
	ds_read_b128 v[204:207], v246 offset:2048
	ds_read_b128 v[242:245], v246 offset:3072
	s_add_i32 s9, s8, 2
	s_lshl_b32 s96, s9, 11
	v_lshl_add_u64 v[248:249], v[184:185], 0, s[96:97]
	v_lshl_add_u64 v[250:251], v[186:187], 0, s[96:97]
	s_waitcnt vmcnt(8) lgkmcnt(3)
	v_mfma_f32_16x16x32_bf16 v[112:115], v[128:131], v[196:199], v[112:115]
	v_mfma_f32_16x16x32_bf16 v[120:123], v[132:135], v[196:199], v[120:123]
	v_mfma_f32_16x16x32_bf16 v[48:51], v[136:139], v[196:199], v[48:51]
	v_mfma_f32_16x16x32_bf16 v[56:59], v[140:143], v[196:199], v[56:59]
	ds_read_b128 v[196:199], v246 offset:4096
	s_waitcnt lgkmcnt(3)
	v_mfma_f32_16x16x32_bf16 v[116:119], v[128:131], v[200:203], v[116:119]
	v_mfma_f32_16x16x32_bf16 v[124:127], v[132:135], v[200:203], v[124:127]
	v_mfma_f32_16x16x32_bf16 v[52:55], v[136:139], v[200:203], v[52:55]
	v_mfma_f32_16x16x32_bf16 v[60:63], v[140:143], v[200:203], v[60:63]
	ds_read_b128 v[200:203], v246 offset:5120
	s_waitcnt lgkmcnt(3)
	v_mfma_f32_16x16x32_bf16 v[96:99], v[128:131], v[204:207], v[96:99]
	v_mfma_f32_16x16x32_bf16 v[104:107], v[132:135], v[204:207], v[104:107]
	v_mfma_f32_16x16x32_bf16 v[32:35], v[136:139], v[204:207], v[32:35]
	v_mfma_f32_16x16x32_bf16 v[40:43], v[140:143], v[204:207], v[40:43]
	ds_read_b128 v[204:207], v246 offset:6144
	s_waitcnt lgkmcnt(3)
	v_mfma_f32_16x16x32_bf16 v[100:103], v[128:131], v[242:245], v[100:103]
	v_mfma_f32_16x16x32_bf16 v[108:111], v[132:135], v[242:245], v[108:111]
	v_mfma_f32_16x16x32_bf16 v[36:39], v[136:139], v[242:245], v[36:39]
	v_mfma_f32_16x16x32_bf16 v[44:47], v[140:143], v[242:245], v[44:47]
	ds_read_b128 v[242:245], v246 offset:7168
	s_waitcnt lgkmcnt(3)
	v_mfma_f32_16x16x32_bf16 v[80:83], v[128:131], v[196:199], v[80:83]
	v_mfma_f32_16x16x32_bf16 v[88:91], v[132:135], v[196:199], v[88:91]
	v_mfma_f32_16x16x32_bf16 v[16:19], v[136:139], v[196:199], v[16:19]
	v_mfma_f32_16x16x32_bf16 v[24:27], v[140:143], v[196:199], v[24:27]
	s_waitcnt lgkmcnt(2)
	v_mfma_f32_16x16x32_bf16 v[84:87], v[128:131], v[200:203], v[84:87]
	v_mfma_f32_16x16x32_bf16 v[92:95], v[132:135], v[200:203], v[92:95]
	v_mfma_f32_16x16x32_bf16 v[20:23], v[136:139], v[200:203], v[20:23]
	v_mfma_f32_16x16x32_bf16 v[28:31], v[140:143], v[200:203], v[28:31]
	s_waitcnt lgkmcnt(1)
	v_mfma_f32_16x16x32_bf16 v[64:67], v[128:131], v[204:207], v[64:67]
	v_mfma_f32_16x16x32_bf16 v[72:75], v[132:135], v[204:207], v[72:75]
	v_mfma_f32_16x16x32_bf16 v[0:3], v[136:139], v[204:207], v[0:3]
	v_mfma_f32_16x16x32_bf16 v[8:11], v[140:143], v[204:207], v[8:11]
	s_waitcnt lgkmcnt(0)
	v_mfma_f32_16x16x32_bf16 v[68:71], v[128:131], v[242:245], v[68:71]
	v_mfma_f32_16x16x32_bf16 v[76:79], v[132:135], v[242:245], v[76:79]
	v_mfma_f32_16x16x32_bf16 v[4:7], v[136:139], v[242:245], v[4:7]
	v_mfma_f32_16x16x32_bf16 v[12:15], v[140:143], v[242:245], v[12:15]
	global_load_dwordx4 v[128:131], v[248:249], off
	global_load_dwordx4 v[132:135], v[248:249], off offset:256
	global_load_dwordx4 v[136:139], v[250:251], off
	global_load_dwordx4 v[140:143], v[250:251], off offset:256
	s_waitcnt vmcnt(10)
	s_barrier
	s_add_i32 s9, s8, 3
	s_lshl_b32 s96, s9, 13
	s_mov_b32 m0, vcc_lo
	v_lshl_add_u64 v[160:161], v[188:189], 0, s[96:97]
	global_load_lds_dwordx4 v[160:161], off
	global_load_lds_dwordx4 v[160:161], off offset:1024
	ds_read_b128 v[196:199], v246 offset:8192
	ds_read_b128 v[200:203], v246 offset:9216
	ds_read_b128 v[204:207], v246 offset:10240
	ds_read_b128 v[242:245], v246 offset:11264
	s_add_i32 s9, s8, 3
	s_lshl_b32 s96, s9, 11
	v_lshl_add_u64 v[248:249], v[184:185], 0, s[96:97]
	v_lshl_add_u64 v[250:251], v[186:187], 0, s[96:97]
	s_waitcnt vmcnt(8) lgkmcnt(3)
	v_mfma_f32_16x16x32_bf16 v[112:115], v[144:147], v[196:199], v[112:115]
	v_mfma_f32_16x16x32_bf16 v[120:123], v[148:151], v[196:199], v[120:123]
	v_mfma_f32_16x16x32_bf16 v[48:51], v[152:155], v[196:199], v[48:51]
	v_mfma_f32_16x16x32_bf16 v[56:59], v[156:159], v[196:199], v[56:59]
	ds_read_b128 v[196:199], v246 offset:12288
	s_waitcnt lgkmcnt(3)
	v_mfma_f32_16x16x32_bf16 v[116:119], v[144:147], v[200:203], v[116:119]
	v_mfma_f32_16x16x32_bf16 v[124:127], v[148:151], v[200:203], v[124:127]
	v_mfma_f32_16x16x32_bf16 v[52:55], v[152:155], v[200:203], v[52:55]
	v_mfma_f32_16x16x32_bf16 v[60:63], v[156:159], v[200:203], v[60:63]
	ds_read_b128 v[200:203], v246 offset:13312
	s_waitcnt lgkmcnt(3)
	v_mfma_f32_16x16x32_bf16 v[96:99], v[144:147], v[204:207], v[96:99]
	v_mfma_f32_16x16x32_bf16 v[104:107], v[148:151], v[204:207], v[104:107]
	v_mfma_f32_16x16x32_bf16 v[32:35], v[152:155], v[204:207], v[32:35]
	v_mfma_f32_16x16x32_bf16 v[40:43], v[156:159], v[204:207], v[40:43]
	ds_read_b128 v[204:207], v246 offset:14336
	s_waitcnt lgkmcnt(3)
	v_mfma_f32_16x16x32_bf16 v[100:103], v[144:147], v[242:245], v[100:103]
	v_mfma_f32_16x16x32_bf16 v[108:111], v[148:151], v[242:245], v[108:111]
	v_mfma_f32_16x16x32_bf16 v[36:39], v[152:155], v[242:245], v[36:39]
	v_mfma_f32_16x16x32_bf16 v[44:47], v[156:159], v[242:245], v[44:47]
	ds_read_b128 v[242:245], v246 offset:15360
	s_waitcnt lgkmcnt(3)
	v_mfma_f32_16x16x32_bf16 v[80:83], v[144:147], v[196:199], v[80:83]
	v_mfma_f32_16x16x32_bf16 v[88:91], v[148:151], v[196:199], v[88:91]
	v_mfma_f32_16x16x32_bf16 v[16:19], v[152:155], v[196:199], v[16:19]
	v_mfma_f32_16x16x32_bf16 v[24:27], v[156:159], v[196:199], v[24:27]
	s_waitcnt lgkmcnt(2)
	v_mfma_f32_16x16x32_bf16 v[84:87], v[144:147], v[200:203], v[84:87]
	v_mfma_f32_16x16x32_bf16 v[92:95], v[148:151], v[200:203], v[92:95]
	v_mfma_f32_16x16x32_bf16 v[20:23], v[152:155], v[200:203], v[20:23]
	v_mfma_f32_16x16x32_bf16 v[28:31], v[156:159], v[200:203], v[28:31]
	s_waitcnt lgkmcnt(1)
	v_mfma_f32_16x16x32_bf16 v[64:67], v[144:147], v[204:207], v[64:67]
	v_mfma_f32_16x16x32_bf16 v[72:75], v[148:151], v[204:207], v[72:75]
	v_mfma_f32_16x16x32_bf16 v[0:3], v[152:155], v[204:207], v[0:3]
	v_mfma_f32_16x16x32_bf16 v[8:11], v[156:159], v[204:207], v[8:11]
	s_waitcnt lgkmcnt(0)
	v_mfma_f32_16x16x32_bf16 v[68:71], v[144:147], v[242:245], v[68:71]
	v_mfma_f32_16x16x32_bf16 v[76:79], v[148:151], v[242:245], v[76:79]
	v_mfma_f32_16x16x32_bf16 v[4:7], v[152:155], v[242:245], v[4:7]
	v_mfma_f32_16x16x32_bf16 v[12:15], v[156:159], v[242:245], v[12:15]
	global_load_dwordx4 v[144:147], v[248:249], off
	global_load_dwordx4 v[148:151], v[248:249], off offset:256
	global_load_dwordx4 v[152:155], v[250:251], off
	global_load_dwordx4 v[156:159], v[250:251], off offset:256
	s_waitcnt vmcnt(10)
	s_barrier
	s_add_i32 s9, s8, 4
	s_lshl_b32 s96, s9, 13
	s_add_i32 m0, vcc_lo, 8192
	v_lshl_add_u64 v[160:161], v[188:189], 0, s[96:97]
	global_load_lds_dwordx4 v[160:161], off
	global_load_lds_dwordx4 v[160:161], off offset:1024
	ds_read_b128 v[196:199], v246 offset:16384
	ds_read_b128 v[200:203], v246 offset:17408
	ds_read_b128 v[204:207], v246 offset:18432
	ds_read_b128 v[242:245], v246 offset:19456
	s_add_i32 s9, s8, 4
	s_lshl_b32 s96, s9, 11
	v_lshl_add_u64 v[248:249], v[184:185], 0, s[96:97]
	v_lshl_add_u64 v[250:251], v[186:187], 0, s[96:97]
	s_waitcnt vmcnt(8) lgkmcnt(3)
	v_mfma_f32_16x16x32_bf16 v[112:115], v[128:131], v[196:199], v[112:115]
	v_mfma_f32_16x16x32_bf16 v[120:123], v[132:135], v[196:199], v[120:123]
	v_mfma_f32_16x16x32_bf16 v[48:51], v[136:139], v[196:199], v[48:51]
	v_mfma_f32_16x16x32_bf16 v[56:59], v[140:143], v[196:199], v[56:59]
	ds_read_b128 v[196:199], v246 offset:20480
	s_waitcnt lgkmcnt(3)
	v_mfma_f32_16x16x32_bf16 v[116:119], v[128:131], v[200:203], v[116:119]
	v_mfma_f32_16x16x32_bf16 v[124:127], v[132:135], v[200:203], v[124:127]
	v_mfma_f32_16x16x32_bf16 v[52:55], v[136:139], v[200:203], v[52:55]
	v_mfma_f32_16x16x32_bf16 v[60:63], v[140:143], v[200:203], v[60:63]
	ds_read_b128 v[200:203], v246 offset:21504
	s_waitcnt lgkmcnt(3)
	v_mfma_f32_16x16x32_bf16 v[96:99], v[128:131], v[204:207], v[96:99]
	v_mfma_f32_16x16x32_bf16 v[104:107], v[132:135], v[204:207], v[104:107]
	v_mfma_f32_16x16x32_bf16 v[32:35], v[136:139], v[204:207], v[32:35]
	v_mfma_f32_16x16x32_bf16 v[40:43], v[140:143], v[204:207], v[40:43]
	ds_read_b128 v[204:207], v246 offset:22528
	s_waitcnt lgkmcnt(3)
	v_mfma_f32_16x16x32_bf16 v[100:103], v[128:131], v[242:245], v[100:103]
	v_mfma_f32_16x16x32_bf16 v[108:111], v[132:135], v[242:245], v[108:111]
	v_mfma_f32_16x16x32_bf16 v[36:39], v[136:139], v[242:245], v[36:39]
	v_mfma_f32_16x16x32_bf16 v[44:47], v[140:143], v[242:245], v[44:47]
	ds_read_b128 v[242:245], v246 offset:23552
	s_waitcnt lgkmcnt(3)
	v_mfma_f32_16x16x32_bf16 v[80:83], v[128:131], v[196:199], v[80:83]
	v_mfma_f32_16x16x32_bf16 v[88:91], v[132:135], v[196:199], v[88:91]
	v_mfma_f32_16x16x32_bf16 v[16:19], v[136:139], v[196:199], v[16:19]
	v_mfma_f32_16x16x32_bf16 v[24:27], v[140:143], v[196:199], v[24:27]
	s_waitcnt lgkmcnt(2)
	v_mfma_f32_16x16x32_bf16 v[84:87], v[128:131], v[200:203], v[84:87]
	v_mfma_f32_16x16x32_bf16 v[92:95], v[132:135], v[200:203], v[92:95]
	v_mfma_f32_16x16x32_bf16 v[20:23], v[136:139], v[200:203], v[20:23]
	v_mfma_f32_16x16x32_bf16 v[28:31], v[140:143], v[200:203], v[28:31]
	s_waitcnt lgkmcnt(1)
	v_mfma_f32_16x16x32_bf16 v[64:67], v[128:131], v[204:207], v[64:67]
	v_mfma_f32_16x16x32_bf16 v[72:75], v[132:135], v[204:207], v[72:75]
	v_mfma_f32_16x16x32_bf16 v[0:3], v[136:139], v[204:207], v[0:3]
	v_mfma_f32_16x16x32_bf16 v[8:11], v[140:143], v[204:207], v[8:11]
	s_waitcnt lgkmcnt(0)
	v_mfma_f32_16x16x32_bf16 v[68:71], v[128:131], v[242:245], v[68:71]
	v_mfma_f32_16x16x32_bf16 v[76:79], v[132:135], v[242:245], v[76:79]
	v_mfma_f32_16x16x32_bf16 v[4:7], v[136:139], v[242:245], v[4:7]
	v_mfma_f32_16x16x32_bf16 v[12:15], v[140:143], v[242:245], v[12:15]
	global_load_dwordx4 v[128:131], v[248:249], off
	global_load_dwordx4 v[132:135], v[248:249], off offset:256
	global_load_dwordx4 v[136:139], v[250:251], off
	global_load_dwordx4 v[140:143], v[250:251], off offset:256
	s_waitcnt vmcnt(10)
	s_barrier
	s_add_i32 s9, s8, 5
	s_lshl_b32 s96, s9, 13
	s_add_i32 m0, vcc_lo, 16384
	v_lshl_add_u64 v[160:161], v[188:189], 0, s[96:97]
	global_load_lds_dwordx4 v[160:161], off
	global_load_lds_dwordx4 v[160:161], off offset:1024
	ds_read_b128 v[196:199], v246 offset:0
	ds_read_b128 v[200:203], v246 offset:1024
	ds_read_b128 v[204:207], v246 offset:2048
	ds_read_b128 v[242:245], v246 offset:3072
	s_add_i32 s9, s8, 5
	s_lshl_b32 s96, s9, 11
	v_lshl_add_u64 v[248:249], v[184:185], 0, s[96:97]
	v_lshl_add_u64 v[250:251], v[186:187], 0, s[96:97]
	s_waitcnt vmcnt(8) lgkmcnt(3)
	v_mfma_f32_16x16x32_bf16 v[112:115], v[144:147], v[196:199], v[112:115]
	v_mfma_f32_16x16x32_bf16 v[120:123], v[148:151], v[196:199], v[120:123]
	v_mfma_f32_16x16x32_bf16 v[48:51], v[152:155], v[196:199], v[48:51]
	v_mfma_f32_16x16x32_bf16 v[56:59], v[156:159], v[196:199], v[56:59]
	ds_read_b128 v[196:199], v246 offset:4096
	s_waitcnt lgkmcnt(3)
	v_mfma_f32_16x16x32_bf16 v[116:119], v[144:147], v[200:203], v[116:119]
	v_mfma_f32_16x16x32_bf16 v[124:127], v[148:151], v[200:203], v[124:127]
	v_mfma_f32_16x16x32_bf16 v[52:55], v[152:155], v[200:203], v[52:55]
	v_mfma_f32_16x16x32_bf16 v[60:63], v[156:159], v[200:203], v[60:63]
	ds_read_b128 v[200:203], v246 offset:5120
	s_waitcnt lgkmcnt(3)
	v_mfma_f32_16x16x32_bf16 v[96:99], v[144:147], v[204:207], v[96:99]
	v_mfma_f32_16x16x32_bf16 v[104:107], v[148:151], v[204:207], v[104:107]
	v_mfma_f32_16x16x32_bf16 v[32:35], v[152:155], v[204:207], v[32:35]
	v_mfma_f32_16x16x32_bf16 v[40:43], v[156:159], v[204:207], v[40:43]
	ds_read_b128 v[204:207], v246 offset:6144
	s_waitcnt lgkmcnt(3)
	v_mfma_f32_16x16x32_bf16 v[100:103], v[144:147], v[242:245], v[100:103]
	v_mfma_f32_16x16x32_bf16 v[108:111], v[148:151], v[242:245], v[108:111]
	v_mfma_f32_16x16x32_bf16 v[36:39], v[152:155], v[242:245], v[36:39]
	v_mfma_f32_16x16x32_bf16 v[44:47], v[156:159], v[242:245], v[44:47]
	ds_read_b128 v[242:245], v246 offset:7168
	s_waitcnt lgkmcnt(3)
	v_mfma_f32_16x16x32_bf16 v[80:83], v[144:147], v[196:199], v[80:83]
	v_mfma_f32_16x16x32_bf16 v[88:91], v[148:151], v[196:199], v[88:91]
	v_mfma_f32_16x16x32_bf16 v[16:19], v[152:155], v[196:199], v[16:19]
	v_mfma_f32_16x16x32_bf16 v[24:27], v[156:159], v[196:199], v[24:27]
	s_waitcnt lgkmcnt(2)
	v_mfma_f32_16x16x32_bf16 v[84:87], v[144:147], v[200:203], v[84:87]
	v_mfma_f32_16x16x32_bf16 v[92:95], v[148:151], v[200:203], v[92:95]
	v_mfma_f32_16x16x32_bf16 v[20:23], v[152:155], v[200:203], v[20:23]
	v_mfma_f32_16x16x32_bf16 v[28:31], v[156:159], v[200:203], v[28:31]
	s_waitcnt lgkmcnt(1)
	v_mfma_f32_16x16x32_bf16 v[64:67], v[144:147], v[204:207], v[64:67]
	v_mfma_f32_16x16x32_bf16 v[72:75], v[148:151], v[204:207], v[72:75]
	v_mfma_f32_16x16x32_bf16 v[0:3], v[152:155], v[204:207], v[0:3]
	v_mfma_f32_16x16x32_bf16 v[8:11], v[156:159], v[204:207], v[8:11]
	s_waitcnt lgkmcnt(0)
	v_mfma_f32_16x16x32_bf16 v[68:71], v[144:147], v[242:245], v[68:71]
	v_mfma_f32_16x16x32_bf16 v[76:79], v[148:151], v[242:245], v[76:79]
	v_mfma_f32_16x16x32_bf16 v[4:7], v[152:155], v[242:245], v[4:7]
	v_mfma_f32_16x16x32_bf16 v[12:15], v[156:159], v[242:245], v[12:15]
	global_load_dwordx4 v[144:147], v[248:249], off
	global_load_dwordx4 v[148:151], v[248:249], off offset:256
	global_load_dwordx4 v[152:155], v[250:251], off
	global_load_dwordx4 v[156:159], v[250:251], off offset:256
	s_waitcnt vmcnt(10)
	s_barrier
	s_add_i32 s9, s8, 6
	s_lshl_b32 s96, s9, 13
	s_mov_b32 m0, vcc_lo
	v_lshl_add_u64 v[160:161], v[188:189], 0, s[96:97]
	global_load_lds_dwordx4 v[160:161], off
	global_load_lds_dwordx4 v[160:161], off offset:1024
	ds_read_b128 v[196:199], v246 offset:8192
	ds_read_b128 v[200:203], v246 offset:9216
	ds_read_b128 v[204:207], v246 offset:10240
	ds_read_b128 v[242:245], v246 offset:11264
	s_add_i32 s9, s8, 6
	s_lshl_b32 s96, s9, 11
	v_lshl_add_u64 v[248:249], v[184:185], 0, s[96:97]
	v_lshl_add_u64 v[250:251], v[186:187], 0, s[96:97]
	s_waitcnt vmcnt(8) lgkmcnt(3)
	v_mfma_f32_16x16x32_bf16 v[112:115], v[128:131], v[196:199], v[112:115]
	v_mfma_f32_16x16x32_bf16 v[120:123], v[132:135], v[196:199], v[120:123]
	v_mfma_f32_16x16x32_bf16 v[48:51], v[136:139], v[196:199], v[48:51]
	v_mfma_f32_16x16x32_bf16 v[56:59], v[140:143], v[196:199], v[56:59]
	ds_read_b128 v[196:199], v246 offset:12288
	s_waitcnt lgkmcnt(3)
	v_mfma_f32_16x16x32_bf16 v[116:119], v[128:131], v[200:203], v[116:119]
	v_mfma_f32_16x16x32_bf16 v[124:127], v[132:135], v[200:203], v[124:127]
	v_mfma_f32_16x16x32_bf16 v[52:55], v[136:139], v[200:203], v[52:55]
	v_mfma_f32_16x16x32_bf16 v[60:63], v[140:143], v[200:203], v[60:63]
	ds_read_b128 v[200:203], v246 offset:13312
	s_waitcnt lgkmcnt(3)
	v_mfma_f32_16x16x32_bf16 v[96:99], v[128:131], v[204:207], v[96:99]
	v_mfma_f32_16x16x32_bf16 v[104:107], v[132:135], v[204:207], v[104:107]
	v_mfma_f32_16x16x32_bf16 v[32:35], v[136:139], v[204:207], v[32:35]
	v_mfma_f32_16x16x32_bf16 v[40:43], v[140:143], v[204:207], v[40:43]
	ds_read_b128 v[204:207], v246 offset:14336
	s_waitcnt lgkmcnt(3)
	v_mfma_f32_16x16x32_bf16 v[100:103], v[128:131], v[242:245], v[100:103]
	v_mfma_f32_16x16x32_bf16 v[108:111], v[132:135], v[242:245], v[108:111]
	v_mfma_f32_16x16x32_bf16 v[36:39], v[136:139], v[242:245], v[36:39]
	v_mfma_f32_16x16x32_bf16 v[44:47], v[140:143], v[242:245], v[44:47]
	ds_read_b128 v[242:245], v246 offset:15360
	s_waitcnt lgkmcnt(3)
	v_mfma_f32_16x16x32_bf16 v[80:83], v[128:131], v[196:199], v[80:83]
	v_mfma_f32_16x16x32_bf16 v[88:91], v[132:135], v[196:199], v[88:91]
	v_mfma_f32_16x16x32_bf16 v[16:19], v[136:139], v[196:199], v[16:19]
	v_mfma_f32_16x16x32_bf16 v[24:27], v[140:143], v[196:199], v[24:27]
	s_waitcnt lgkmcnt(2)
	v_mfma_f32_16x16x32_bf16 v[84:87], v[128:131], v[200:203], v[84:87]
	v_mfma_f32_16x16x32_bf16 v[92:95], v[132:135], v[200:203], v[92:95]
	v_mfma_f32_16x16x32_bf16 v[20:23], v[136:139], v[200:203], v[20:23]
	v_mfma_f32_16x16x32_bf16 v[28:31], v[140:143], v[200:203], v[28:31]
	s_waitcnt lgkmcnt(1)
	v_mfma_f32_16x16x32_bf16 v[64:67], v[128:131], v[204:207], v[64:67]
	v_mfma_f32_16x16x32_bf16 v[72:75], v[132:135], v[204:207], v[72:75]
	v_mfma_f32_16x16x32_bf16 v[0:3], v[136:139], v[204:207], v[0:3]
	v_mfma_f32_16x16x32_bf16 v[8:11], v[140:143], v[204:207], v[8:11]
	s_waitcnt lgkmcnt(0)
	v_mfma_f32_16x16x32_bf16 v[68:71], v[128:131], v[242:245], v[68:71]
	v_mfma_f32_16x16x32_bf16 v[76:79], v[132:135], v[242:245], v[76:79]
	v_mfma_f32_16x16x32_bf16 v[4:7], v[136:139], v[242:245], v[4:7]
	v_mfma_f32_16x16x32_bf16 v[12:15], v[140:143], v[242:245], v[12:15]
	global_load_dwordx4 v[128:131], v[248:249], off
	global_load_dwordx4 v[132:135], v[248:249], off offset:256
	global_load_dwordx4 v[136:139], v[250:251], off
	global_load_dwordx4 v[140:143], v[250:251], off offset:256
	s_waitcnt vmcnt(10)
	s_barrier
	s_add_i32 s9, s8, 7
	s_lshl_b32 s96, s9, 13
	s_add_i32 m0, vcc_lo, 8192
	v_lshl_add_u64 v[160:161], v[188:189], 0, s[96:97]
	global_load_lds_dwordx4 v[160:161], off
	global_load_lds_dwordx4 v[160:161], off offset:1024
	ds_read_b128 v[196:199], v246 offset:16384
	ds_read_b128 v[200:203], v246 offset:17408
	ds_read_b128 v[204:207], v246 offset:18432
	ds_read_b128 v[242:245], v246 offset:19456
	s_add_i32 s9, s8, 7
	s_lshl_b32 s96, s9, 11
	v_lshl_add_u64 v[248:249], v[184:185], 0, s[96:97]
	v_lshl_add_u64 v[250:251], v[186:187], 0, s[96:97]
	s_waitcnt vmcnt(8) lgkmcnt(3)
	v_mfma_f32_16x16x32_bf16 v[112:115], v[144:147], v[196:199], v[112:115]
	v_mfma_f32_16x16x32_bf16 v[120:123], v[148:151], v[196:199], v[120:123]
	v_mfma_f32_16x16x32_bf16 v[48:51], v[152:155], v[196:199], v[48:51]
	v_mfma_f32_16x16x32_bf16 v[56:59], v[156:159], v[196:199], v[56:59]
	ds_read_b128 v[196:199], v246 offset:20480
	s_waitcnt lgkmcnt(3)
	v_mfma_f32_16x16x32_bf16 v[116:119], v[144:147], v[200:203], v[116:119]
	v_mfma_f32_16x16x32_bf16 v[124:127], v[148:151], v[200:203], v[124:127]
	v_mfma_f32_16x16x32_bf16 v[52:55], v[152:155], v[200:203], v[52:55]
	v_mfma_f32_16x16x32_bf16 v[60:63], v[156:159], v[200:203], v[60:63]
	ds_read_b128 v[200:203], v246 offset:21504
	s_waitcnt lgkmcnt(3)
	v_mfma_f32_16x16x32_bf16 v[96:99], v[144:147], v[204:207], v[96:99]
	v_mfma_f32_16x16x32_bf16 v[104:107], v[148:151], v[204:207], v[104:107]
	v_mfma_f32_16x16x32_bf16 v[32:35], v[152:155], v[204:207], v[32:35]
	v_mfma_f32_16x16x32_bf16 v[40:43], v[156:159], v[204:207], v[40:43]
	ds_read_b128 v[204:207], v246 offset:22528
	s_waitcnt lgkmcnt(3)
	v_mfma_f32_16x16x32_bf16 v[100:103], v[144:147], v[242:245], v[100:103]
	v_mfma_f32_16x16x32_bf16 v[108:111], v[148:151], v[242:245], v[108:111]
	v_mfma_f32_16x16x32_bf16 v[36:39], v[152:155], v[242:245], v[36:39]
	v_mfma_f32_16x16x32_bf16 v[44:47], v[156:159], v[242:245], v[44:47]
	ds_read_b128 v[242:245], v246 offset:23552
	s_waitcnt lgkmcnt(3)
	v_mfma_f32_16x16x32_bf16 v[80:83], v[144:147], v[196:199], v[80:83]
	v_mfma_f32_16x16x32_bf16 v[88:91], v[148:151], v[196:199], v[88:91]
	v_mfma_f32_16x16x32_bf16 v[16:19], v[152:155], v[196:199], v[16:19]
	v_mfma_f32_16x16x32_bf16 v[24:27], v[156:159], v[196:199], v[24:27]
	s_waitcnt lgkmcnt(2)
	v_mfma_f32_16x16x32_bf16 v[84:87], v[144:147], v[200:203], v[84:87]
	v_mfma_f32_16x16x32_bf16 v[92:95], v[148:151], v[200:203], v[92:95]
	v_mfma_f32_16x16x32_bf16 v[20:23], v[152:155], v[200:203], v[20:23]
	v_mfma_f32_16x16x32_bf16 v[28:31], v[156:159], v[200:203], v[28:31]
	s_waitcnt lgkmcnt(1)
	v_mfma_f32_16x16x32_bf16 v[64:67], v[144:147], v[204:207], v[64:67]
	v_mfma_f32_16x16x32_bf16 v[72:75], v[148:151], v[204:207], v[72:75]
	v_mfma_f32_16x16x32_bf16 v[0:3], v[152:155], v[204:207], v[0:3]
	v_mfma_f32_16x16x32_bf16 v[8:11], v[156:159], v[204:207], v[8:11]
	s_waitcnt lgkmcnt(0)
	v_mfma_f32_16x16x32_bf16 v[68:71], v[144:147], v[242:245], v[68:71]
	v_mfma_f32_16x16x32_bf16 v[76:79], v[148:151], v[242:245], v[76:79]
	v_mfma_f32_16x16x32_bf16 v[4:7], v[152:155], v[242:245], v[4:7]
	v_mfma_f32_16x16x32_bf16 v[12:15], v[156:159], v[242:245], v[12:15]
	global_load_dwordx4 v[144:147], v[248:249], off
	global_load_dwordx4 v[148:151], v[248:249], off offset:256
	global_load_dwordx4 v[152:155], v[250:251], off
	global_load_dwordx4 v[156:159], v[250:251], off offset:256
	s_waitcnt vmcnt(10)
	s_barrier
	s_add_i32 s8, s8, 6
	s_cmp_lt_u32 s8, 84
	s_cbranch_scc1 .Lg16_down_k
	s_mov_b32 s96, 0xac000
	s_add_i32 m0, vcc_lo, 16384
	v_lshl_add_u64 v[160:161], v[188:189], 0, s[96:97]
	global_load_lds_dwordx4 v[160:161], off
	global_load_lds_dwordx4 v[160:161], off offset:1024
	ds_read_b128 v[196:199], v246 offset:0
	ds_read_b128 v[200:203], v246 offset:1024
	ds_read_b128 v[204:207], v246 offset:2048
	ds_read_b128 v[242:245], v246 offset:3072
	s_mov_b32 s96, 0x2b000
	v_lshl_add_u64 v[248:249], v[184:185], 0, s[96:97]
	v_lshl_add_u64 v[250:251], v[186:187], 0, s[96:97]
	s_waitcnt vmcnt(8) lgkmcnt(3)
	v_mfma_f32_16x16x32_bf16 v[112:115], v[128:131], v[196:199], v[112:115]
	v_mfma_f32_16x16x32_bf16 v[120:123], v[132:135], v[196:199], v[120:123]
	v_mfma_f32_16x16x32_bf16 v[48:51], v[136:139], v[196:199], v[48:51]
	v_mfma_f32_16x16x32_bf16 v[56:59], v[140:143], v[196:199], v[56:59]
	ds_read_b128 v[196:199], v246 offset:4096
	s_waitcnt lgkmcnt(3)
	v_mfma_f32_16x16x32_bf16 v[116:119], v[128:131], v[200:203], v[116:119]
	v_mfma_f32_16x16x32_bf16 v[124:127], v[132:135], v[200:203], v[124:127]
	v_mfma_f32_16x16x32_bf16 v[52:55], v[136:139], v[200:203], v[52:55]
	v_mfma_f32_16x16x32_bf16 v[60:63], v[140:143], v[200:203], v[60:63]
	ds_read_b128 v[200:203], v246 offset:5120
	s_waitcnt lgkmcnt(3)
	v_mfma_f32_16x16x32_bf16 v[96:99], v[128:131], v[204:207], v[96:99]
	v_mfma_f32_16x16x32_bf16 v[104:107], v[132:135], v[204:207], v[104:107]
	v_mfma_f32_16x16x32_bf16 v[32:35], v[136:139], v[204:207], v[32:35]
	v_mfma_f32_16x16x32_bf16 v[40:43], v[140:143], v[204:207], v[40:43]
	ds_read_b128 v[204:207], v246 offset:6144
	s_waitcnt lgkmcnt(3)
	v_mfma_f32_16x16x32_bf16 v[100:103], v[128:131], v[242:245], v[100:103]
	v_mfma_f32_16x16x32_bf16 v[108:111], v[132:135], v[242:245], v[108:111]
	v_mfma_f32_16x16x32_bf16 v[36:39], v[136:139], v[242:245], v[36:39]
	v_mfma_f32_16x16x32_bf16 v[44:47], v[140:143], v[242:245], v[44:47]
	ds_read_b128 v[242:245], v246 offset:7168
	s_waitcnt lgkmcnt(3)
	v_mfma_f32_16x16x32_bf16 v[80:83], v[128:131], v[196:199], v[80:83]
	v_mfma_f32_16x16x32_bf16 v[88:91], v[132:135], v[196:199], v[88:91]
	v_mfma_f32_16x16x32_bf16 v[16:19], v[136:139], v[196:199], v[16:19]
	v_mfma_f32_16x16x32_bf16 v[24:27], v[140:143], v[196:199], v[24:27]
	s_waitcnt lgkmcnt(2)
	v_mfma_f32_16x16x32_bf16 v[84:87], v[128:131], v[200:203], v[84:87]
	v_mfma_f32_16x16x32_bf16 v[92:95], v[132:135], v[200:203], v[92:95]
	v_mfma_f32_16x16x32_bf16 v[20:23], v[136:139], v[200:203], v[20:23]
	v_mfma_f32_16x16x32_bf16 v[28:31], v[140:143], v[200:203], v[28:31]
	s_waitcnt lgkmcnt(1)
	v_mfma_f32_16x16x32_bf16 v[64:67], v[128:131], v[204:207], v[64:67]
	v_mfma_f32_16x16x32_bf16 v[72:75], v[132:135], v[204:207], v[72:75]
	v_mfma_f32_16x16x32_bf16 v[0:3], v[136:139], v[204:207], v[0:3]
	v_mfma_f32_16x16x32_bf16 v[8:11], v[140:143], v[204:207], v[8:11]
	s_waitcnt lgkmcnt(0)
	v_mfma_f32_16x16x32_bf16 v[68:71], v[128:131], v[242:245], v[68:71]
	v_mfma_f32_16x16x32_bf16 v[76:79], v[132:135], v[242:245], v[76:79]
	v_mfma_f32_16x16x32_bf16 v[4:7], v[136:139], v[242:245], v[4:7]
	v_mfma_f32_16x16x32_bf16 v[12:15], v[140:143], v[242:245], v[12:15]
	global_load_dwordx4 v[128:131], v[248:249], off
	global_load_dwordx4 v[132:135], v[248:249], off offset:256
	global_load_dwordx4 v[136:139], v[250:251], off
	global_load_dwordx4 v[140:143], v[250:251], off offset:256
	s_waitcnt vmcnt(10)
	s_barrier
	s_mov_b32 s96, 0xae000
	s_mov_b32 m0, vcc_lo
	v_lshl_add_u64 v[160:161], v[188:189], 0, s[96:97]
	global_load_lds_dwordx4 v[160:161], off
	global_load_lds_dwordx4 v[160:161], off offset:1024
	ds_read_b128 v[196:199], v246 offset:8192
	ds_read_b128 v[200:203], v246 offset:9216
	ds_read_b128 v[204:207], v246 offset:10240
	ds_read_b128 v[242:245], v246 offset:11264
	s_mov_b32 s96, 0x2b800
	v_lshl_add_u64 v[248:249], v[184:185], 0, s[96:97]
	v_lshl_add_u64 v[250:251], v[186:187], 0, s[96:97]
	s_waitcnt vmcnt(8) lgkmcnt(3)
	v_mfma_f32_16x16x32_bf16 v[112:115], v[144:147], v[196:199], v[112:115]
	v_mfma_f32_16x16x32_bf16 v[120:123], v[148:151], v[196:199], v[120:123]
	v_mfma_f32_16x16x32_bf16 v[48:51], v[152:155], v[196:199], v[48:51]
	v_mfma_f32_16x16x32_bf16 v[56:59], v[156:159], v[196:199], v[56:59]
	ds_read_b128 v[196:199], v246 offset:12288
	s_waitcnt lgkmcnt(3)
	v_mfma_f32_16x16x32_bf16 v[116:119], v[144:147], v[200:203], v[116:119]
	v_mfma_f32_16x16x32_bf16 v[124:127], v[148:151], v[200:203], v[124:127]
	v_mfma_f32_16x16x32_bf16 v[52:55], v[152:155], v[200:203], v[52:55]
	v_mfma_f32_16x16x32_bf16 v[60:63], v[156:159], v[200:203], v[60:63]
	ds_read_b128 v[200:203], v246 offset:13312
	s_waitcnt lgkmcnt(3)
	v_mfma_f32_16x16x32_bf16 v[96:99], v[144:147], v[204:207], v[96:99]
	v_mfma_f32_16x16x32_bf16 v[104:107], v[148:151], v[204:207], v[104:107]
	v_mfma_f32_16x16x32_bf16 v[32:35], v[152:155], v[204:207], v[32:35]
	v_mfma_f32_16x16x32_bf16 v[40:43], v[156:159], v[204:207], v[40:43]
	ds_read_b128 v[204:207], v246 offset:14336
	s_waitcnt lgkmcnt(3)
	v_mfma_f32_16x16x32_bf16 v[100:103], v[144:147], v[242:245], v[100:103]
	v_mfma_f32_16x16x32_bf16 v[108:111], v[148:151], v[242:245], v[108:111]
	v_mfma_f32_16x16x32_bf16 v[36:39], v[152:155], v[242:245], v[36:39]
	v_mfma_f32_16x16x32_bf16 v[44:47], v[156:159], v[242:245], v[44:47]
	ds_read_b128 v[242:245], v246 offset:15360
	s_waitcnt lgkmcnt(3)
	v_mfma_f32_16x16x32_bf16 v[80:83], v[144:147], v[196:199], v[80:83]
	v_mfma_f32_16x16x32_bf16 v[88:91], v[148:151], v[196:199], v[88:91]
	v_mfma_f32_16x16x32_bf16 v[16:19], v[152:155], v[196:199], v[16:19]
	v_mfma_f32_16x16x32_bf16 v[24:27], v[156:159], v[196:199], v[24:27]
	s_waitcnt lgkmcnt(2)
	v_mfma_f32_16x16x32_bf16 v[84:87], v[144:147], v[200:203], v[84:87]
	v_mfma_f32_16x16x32_bf16 v[92:95], v[148:151], v[200:203], v[92:95]
	v_mfma_f32_16x16x32_bf16 v[20:23], v[152:155], v[200:203], v[20:23]
	v_mfma_f32_16x16x32_bf16 v[28:31], v[156:159], v[200:203], v[28:31]
	s_waitcnt lgkmcnt(1)
	v_mfma_f32_16x16x32_bf16 v[64:67], v[144:147], v[204:207], v[64:67]
	v_mfma_f32_16x16x32_bf16 v[72:75], v[148:151], v[204:207], v[72:75]
	v_mfma_f32_16x16x32_bf16 v[0:3], v[152:155], v[204:207], v[0:3]
	v_mfma_f32_16x16x32_bf16 v[8:11], v[156:159], v[204:207], v[8:11]
	s_waitcnt lgkmcnt(0)
	v_mfma_f32_16x16x32_bf16 v[68:71], v[144:147], v[242:245], v[68:71]
	v_mfma_f32_16x16x32_bf16 v[76:79], v[148:151], v[242:245], v[76:79]
	v_mfma_f32_16x16x32_bf16 v[4:7], v[152:155], v[242:245], v[4:7]
	v_mfma_f32_16x16x32_bf16 v[12:15], v[156:159], v[242:245], v[12:15]
	global_load_dwordx4 v[144:147], v[248:249], off
	global_load_dwordx4 v[148:151], v[248:249], off offset:256
	global_load_dwordx4 v[152:155], v[250:251], off
	global_load_dwordx4 v[156:159], v[250:251], off offset:256
	s_waitcnt vmcnt(10)
	s_barrier
	ds_read_b128 v[196:199], v246 offset:16384
	ds_read_b128 v[200:203], v246 offset:17408
	ds_read_b128 v[204:207], v246 offset:18432
	ds_read_b128 v[242:245], v246 offset:19456
	s_waitcnt vmcnt(6) lgkmcnt(3)
	v_mfma_f32_16x16x32_bf16 v[112:115], v[128:131], v[196:199], v[112:115]
	v_mfma_f32_16x16x32_bf16 v[120:123], v[132:135], v[196:199], v[120:123]
	v_mfma_f32_16x16x32_bf16 v[48:51], v[136:139], v[196:199], v[48:51]
	v_mfma_f32_16x16x32_bf16 v[56:59], v[140:143], v[196:199], v[56:59]
	ds_read_b128 v[196:199], v246 offset:20480
	s_waitcnt lgkmcnt(3)
	v_mfma_f32_16x16x32_bf16 v[116:119], v[128:131], v[200:203], v[116:119]
	v_mfma_f32_16x16x32_bf16 v[124:127], v[132:135], v[200:203], v[124:127]
	v_mfma_f32_16x16x32_bf16 v[52:55], v[136:139], v[200:203], v[52:55]
	v_mfma_f32_16x16x32_bf16 v[60:63], v[140:143], v[200:203], v[60:63]
	ds_read_b128 v[200:203], v246 offset:21504
	s_waitcnt lgkmcnt(3)
	v_mfma_f32_16x16x32_bf16 v[96:99], v[128:131], v[204:207], v[96:99]
	v_mfma_f32_16x16x32_bf16 v[104:107], v[132:135], v[204:207], v[104:107]
	v_mfma_f32_16x16x32_bf16 v[32:35], v[136:139], v[204:207], v[32:35]
	v_mfma_f32_16x16x32_bf16 v[40:43], v[140:143], v[204:207], v[40:43]
	ds_read_b128 v[204:207], v246 offset:22528
	s_waitcnt lgkmcnt(3)
	v_mfma_f32_16x16x32_bf16 v[100:103], v[128:131], v[242:245], v[100:103]
	v_mfma_f32_16x16x32_bf16 v[108:111], v[132:135], v[242:245], v[108:111]
	v_mfma_f32_16x16x32_bf16 v[36:39], v[136:139], v[242:245], v[36:39]
	v_mfma_f32_16x16x32_bf16 v[44:47], v[140:143], v[242:245], v[44:47]
	ds_read_b128 v[242:245], v246 offset:23552
	s_waitcnt lgkmcnt(3)
	v_mfma_f32_16x16x32_bf16 v[80:83], v[128:131], v[196:199], v[80:83]
	v_mfma_f32_16x16x32_bf16 v[88:91], v[132:135], v[196:199], v[88:91]
	v_mfma_f32_16x16x32_bf16 v[16:19], v[136:139], v[196:199], v[16:19]
	v_mfma_f32_16x16x32_bf16 v[24:27], v[140:143], v[196:199], v[24:27]
	s_waitcnt lgkmcnt(2)
	v_mfma_f32_16x16x32_bf16 v[84:87], v[128:131], v[200:203], v[84:87]
	v_mfma_f32_16x16x32_bf16 v[92:95], v[132:135], v[200:203], v[92:95]
	v_mfma_f32_16x16x32_bf16 v[20:23], v[136:139], v[200:203], v[20:23]
	v_mfma_f32_16x16x32_bf16 v[28:31], v[140:143], v[200:203], v[28:31]
	s_waitcnt lgkmcnt(1)
	v_mfma_f32_16x16x32_bf16 v[64:67], v[128:131], v[204:207], v[64:67]
	v_mfma_f32_16x16x32_bf16 v[72:75], v[132:135], v[204:207], v[72:75]
	v_mfma_f32_16x16x32_bf16 v[0:3], v[136:139], v[204:207], v[0:3]
	v_mfma_f32_16x16x32_bf16 v[8:11], v[140:143], v[204:207], v[8:11]
	s_waitcnt lgkmcnt(0)
	v_mfma_f32_16x16x32_bf16 v[68:71], v[128:131], v[242:245], v[68:71]
	v_mfma_f32_16x16x32_bf16 v[76:79], v[132:135], v[242:245], v[76:79]
	v_mfma_f32_16x16x32_bf16 v[4:7], v[136:139], v[242:245], v[4:7]
	v_mfma_f32_16x16x32_bf16 v[12:15], v[140:143], v[242:245], v[12:15]
	s_waitcnt vmcnt(4)
	s_barrier
	ds_read_b128 v[196:199], v246 offset:0
	ds_read_b128 v[200:203], v246 offset:1024
	ds_read_b128 v[204:207], v246 offset:2048
	ds_read_b128 v[242:245], v246 offset:3072
	s_waitcnt vmcnt(0) lgkmcnt(3)
	v_mfma_f32_16x16x32_bf16 v[112:115], v[144:147], v[196:199], v[112:115]
	v_mfma_f32_16x16x32_bf16 v[120:123], v[148:151], v[196:199], v[120:123]
	v_mfma_f32_16x16x32_bf16 v[48:51], v[152:155], v[196:199], v[48:51]
	v_mfma_f32_16x16x32_bf16 v[56:59], v[156:159], v[196:199], v[56:59]
	ds_read_b128 v[196:199], v246 offset:4096
	s_waitcnt lgkmcnt(3)
	v_mfma_f32_16x16x32_bf16 v[116:119], v[144:147], v[200:203], v[116:119]
	v_mfma_f32_16x16x32_bf16 v[124:127], v[148:151], v[200:203], v[124:127]
	v_mfma_f32_16x16x32_bf16 v[52:55], v[152:155], v[200:203], v[52:55]
	v_mfma_f32_16x16x32_bf16 v[60:63], v[156:159], v[200:203], v[60:63]
	ds_read_b128 v[200:203], v246 offset:5120
	s_waitcnt lgkmcnt(3)
	v_mfma_f32_16x16x32_bf16 v[96:99], v[144:147], v[204:207], v[96:99]
	v_mfma_f32_16x16x32_bf16 v[104:107], v[148:151], v[204:207], v[104:107]
	v_mfma_f32_16x16x32_bf16 v[32:35], v[152:155], v[204:207], v[32:35]
	v_mfma_f32_16x16x32_bf16 v[40:43], v[156:159], v[204:207], v[40:43]
	ds_read_b128 v[204:207], v246 offset:6144
	s_waitcnt lgkmcnt(3)
	v_mfma_f32_16x16x32_bf16 v[100:103], v[144:147], v[242:245], v[100:103]
	v_mfma_f32_16x16x32_bf16 v[108:111], v[148:151], v[242:245], v[108:111]
	v_mfma_f32_16x16x32_bf16 v[36:39], v[152:155], v[242:245], v[36:39]
	v_mfma_f32_16x16x32_bf16 v[44:47], v[156:159], v[242:245], v[44:47]
	ds_read_b128 v[242:245], v246 offset:7168
	v_permlane16_swap_b32_e32 v112, v116
	v_permlane16_swap_b32_e32 v113, v117
	v_permlane16_swap_b32_e32 v114, v118
	v_permlane16_swap_b32_e32 v115, v119
	v_permlane16_swap_b32_e32 v120, v124
	v_permlane16_swap_b32_e32 v121, v125
	v_permlane16_swap_b32_e32 v122, v126
	v_permlane16_swap_b32_e32 v123, v127
	v_permlane16_swap_b32_e32 v48, v52
	v_permlane16_swap_b32_e32 v49, v53
	v_permlane16_swap_b32_e32 v50, v54
	v_permlane16_swap_b32_e32 v51, v55
	v_permlane16_swap_b32_e32 v56, v60
	v_permlane16_swap_b32_e32 v57, v61
	v_permlane16_swap_b32_e32 v58, v62
	v_permlane16_swap_b32_e32 v59, v63
	v_permlane32_swap_b32_e32 v112, v116
	v_permlane32_swap_b32_e32 v113, v117
	v_permlane32_swap_b32_e32 v114, v118
	v_permlane32_swap_b32_e32 v115, v119
	v_permlane32_swap_b32_e32 v120, v124
	v_permlane32_swap_b32_e32 v121, v125
	v_permlane32_swap_b32_e32 v122, v126
	v_permlane32_swap_b32_e32 v123, v127
	v_permlane32_swap_b32_e32 v48, v52
	v_permlane32_swap_b32_e32 v49, v53
	v_permlane32_swap_b32_e32 v50, v54
	v_permlane32_swap_b32_e32 v51, v55
	v_permlane32_swap_b32_e32 v56, v60
	v_permlane32_swap_b32_e32 v57, v61
	v_permlane32_swap_b32_e32 v58, v62
	v_permlane32_swap_b32_e32 v59, v63
	s_waitcnt lgkmcnt(3)
	v_mfma_f32_16x16x32_bf16 v[80:83], v[144:147], v[196:199], v[80:83]
	v_mfma_f32_16x16x32_bf16 v[88:91], v[148:151], v[196:199], v[88:91]
	v_mfma_f32_16x16x32_bf16 v[16:19], v[152:155], v[196:199], v[16:19]
	v_mfma_f32_16x16x32_bf16 v[24:27], v[156:159], v[196:199], v[24:27]
	s_waitcnt lgkmcnt(2)
	v_mfma_f32_16x16x32_bf16 v[84:87], v[144:147], v[200:203], v[84:87]
	v_mfma_f32_16x16x32_bf16 v[92:95], v[148:151], v[200:203], v[92:95]
	v_mfma_f32_16x16x32_bf16 v[20:23], v[152:155], v[200:203], v[20:23]
	v_mfma_f32_16x16x32_bf16 v[28:31], v[156:159], v[200:203], v[28:31]
	v_permlane16_swap_b32_e32 v96, v100
	v_permlane16_swap_b32_e32 v97, v101
	v_permlane16_swap_b32_e32 v98, v102
	v_permlane16_swap_b32_e32 v99, v103
	v_permlane16_swap_b32_e32 v104, v108
	v_permlane16_swap_b32_e32 v105, v109
	v_permlane16_swap_b32_e32 v106, v110
	v_permlane16_swap_b32_e32 v107, v111
	v_permlane16_swap_b32_e32 v32, v36
	v_permlane16_swap_b32_e32 v33, v37
	v_permlane16_swap_b32_e32 v34, v38
	v_permlane16_swap_b32_e32 v35, v39
	v_permlane16_swap_b32_e32 v40, v44
	v_permlane16_swap_b32_e32 v41, v45
	v_permlane16_swap_b32_e32 v42, v46
	v_permlane16_swap_b32_e32 v43, v47
	v_permlane32_swap_b32_e32 v96, v100
	v_permlane32_swap_b32_e32 v97, v101
	v_permlane32_swap_b32_e32 v98, v102
	v_permlane32_swap_b32_e32 v99, v103
	v_permlane32_swap_b32_e32 v104, v108
	v_permlane32_swap_b32_e32 v105, v109
	v_permlane32_swap_b32_e32 v106, v110
	v_permlane32_swap_b32_e32 v107, v111
	v_permlane32_swap_b32_e32 v32, v36
	v_permlane32_swap_b32_e32 v33, v37
	v_permlane32_swap_b32_e32 v34, v38
	v_permlane32_swap_b32_e32 v35, v39
	v_permlane32_swap_b32_e32 v40, v44
	v_permlane32_swap_b32_e32 v41, v45
	v_permlane32_swap_b32_e32 v42, v46
	v_permlane32_swap_b32_e32 v43, v47
	s_waitcnt lgkmcnt(1)
	v_mfma_f32_16x16x32_bf16 v[64:67], v[144:147], v[204:207], v[64:67]
	v_mfma_f32_16x16x32_bf16 v[72:75], v[148:151], v[204:207], v[72:75]
	v_mfma_f32_16x16x32_bf16 v[0:3], v[152:155], v[204:207], v[0:3]
	v_mfma_f32_16x16x32_bf16 v[8:11], v[156:159], v[204:207], v[8:11]
	s_waitcnt lgkmcnt(0)
	v_mfma_f32_16x16x32_bf16 v[68:71], v[144:147], v[242:245], v[68:71]
	v_mfma_f32_16x16x32_bf16 v[76:79], v[148:151], v[242:245], v[76:79]
	v_mfma_f32_16x16x32_bf16 v[4:7], v[152:155], v[242:245], v[4:7]
	v_mfma_f32_16x16x32_bf16 v[12:15], v[156:159], v[242:245], v[12:15]
	v_permlane16_swap_b32_e32 v80, v84
	v_permlane16_swap_b32_e32 v81, v85
	v_permlane16_swap_b32_e32 v82, v86
	v_permlane16_swap_b32_e32 v83, v87
	v_permlane16_swap_b32_e32 v88, v92
	v_permlane16_swap_b32_e32 v89, v93
	v_permlane16_swap_b32_e32 v90, v94
	v_permlane16_swap_b32_e32 v91, v95
	v_permlane16_swap_b32_e32 v16, v20
	v_permlane16_swap_b32_e32 v17, v21
	v_permlane16_swap_b32_e32 v18, v22
	v_permlane16_swap_b32_e32 v19, v23
	v_permlane16_swap_b32_e32 v24, v28
	v_permlane16_swap_b32_e32 v25, v29
	v_permlane16_swap_b32_e32 v26, v30
	v_permlane16_swap_b32_e32 v27, v31
	v_permlane32_swap_b32_e32 v80, v84
	v_permlane32_swap_b32_e32 v81, v85
	v_permlane32_swap_b32_e32 v82, v86
	v_permlane32_swap_b32_e32 v83, v87
	v_permlane32_swap_b32_e32 v88, v92
	v_permlane32_swap_b32_e32 v89, v93
	v_permlane32_swap_b32_e32 v90, v94
	v_permlane32_swap_b32_e32 v91, v95
	v_permlane32_swap_b32_e32 v16, v20
	v_permlane32_swap_b32_e32 v17, v21
	v_permlane32_swap_b32_e32 v18, v22
	v_permlane32_swap_b32_e32 v19, v23
	v_permlane32_swap_b32_e32 v24, v28
	v_permlane32_swap_b32_e32 v25, v29
	v_permlane32_swap_b32_e32 v26, v30
	v_permlane32_swap_b32_e32 v27, v31
	s_barrier
	s_nop 7
	v_permlane16_swap_b32_e32 v64, v68
	v_permlane16_swap_b32_e32 v65, v69
	v_permlane16_swap_b32_e32 v66, v70
	v_permlane16_swap_b32_e32 v67, v71
	v_permlane16_swap_b32_e32 v72, v76
	v_permlane16_swap_b32_e32 v73, v77
	v_permlane16_swap_b32_e32 v74, v78
	v_permlane16_swap_b32_e32 v75, v79
	v_permlane16_swap_b32_e32 v0, v4
	v_permlane16_swap_b32_e32 v1, v5
	v_permlane16_swap_b32_e32 v2, v6
	v_permlane16_swap_b32_e32 v3, v7
	v_permlane16_swap_b32_e32 v8, v12
	v_permlane16_swap_b32_e32 v9, v13
	v_permlane16_swap_b32_e32 v10, v14
	v_permlane16_swap_b32_e32 v11, v15
	v_permlane32_swap_b32_e32 v64, v68
	v_permlane32_swap_b32_e32 v65, v69
	v_permlane32_swap_b32_e32 v66, v70
	v_permlane32_swap_b32_e32 v67, v71
	v_permlane32_swap_b32_e32 v72, v76
	v_permlane32_swap_b32_e32 v73, v77
	v_permlane32_swap_b32_e32 v74, v78
	v_permlane32_swap_b32_e32 v75, v79
	v_permlane32_swap_b32_e32 v0, v4
	v_permlane32_swap_b32_e32 v1, v5
	v_permlane32_swap_b32_e32 v2, v6
	v_permlane32_swap_b32_e32 v3, v7
	v_permlane32_swap_b32_e32 v8, v12
	v_permlane32_swap_b32_e32 v9, v13
	v_permlane32_swap_b32_e32 v10, v14
	v_permlane32_swap_b32_e32 v11, v15
	s_waitcnt vmcnt(0)
	s_waitcnt vmcnt(0)
	v_and_b32_e32 v188, 63, v179
	v_lshrrev_b32_e32 v189, 6, v179
	v_mul_u32_u24_e32 v249, 0x2400, v189
	v_mov_b32_e32 v250, v249
	v_lshrrev_b32_e32 v251, 5, v188
	v_mul_u32_u24_e32 v251, 0x440, v251
	v_add_u32_e32 v249, v249, v251
	v_and_b32_e32 v251, 31, v188
	v_lshl_add_u32 v249, v251, 2, v249
	v_lshrrev_b32_e32 v237, 4, v188
	v_mul_u32_u24_e32 v251, 0x110, v237
	v_add_u32_e32 v250, v250, v251
	v_and_b32_e32 v251, 15, v188
	v_lshlrev_b32_e32 v251, 4, v251
	v_add_u32_e32 v250, v250, v251
	v_lshl_add_u32 v237, v189, 6, v237
	v_lshl_add_u32 v237, v237, 12, v251
	v_add_u32_e32 v238, 16384, v237
	v_add_u32_e32 v239, 32768, v237
	v_add_u32_e32 v240, 49152, v237
	v_add_u32_e32 v241, 65536, v237
	v_add_u32_e32 v242, 81920, v237
	v_add_u32_e32 v243, 98304, v237
	v_add_u32_e32 v248, 114688, v237
	s_lshl_b32 s16, s7, 8
	s_lshl_b32 s18, s6, 9
	s_lshr_b32 s19, s7, 4
	v_readlane_b32 s12, v253, 46
	v_readlane_b32 s13, v253, 47
	v_readlane_b32 s14, v253, 46
	v_readlane_b32 s15, v253, 47
	s_add_i32 s17, s16, 0xffff8000
	s_cmpk_lt_u32 s7, 0x80
	s_cselect_b32 s12, s12, s62
	s_cselect_b32 s13, s13, s63
	s_cselect_b32 s14, s14, s62
	s_cselect_b32 s15, s15, s63
	s_cselect_b32 s19, s19, 8
	s_cselect_b32 s16, s16, s17
	s_mov_b32 s17, 0
	s_lshl_b64 s[16:17], s[16:17], 12
	s_add_u32 s16, s16, s18
	s_addc_u32 s17, s17, 0
	s_add_u32 s12, s12, s16
	s_addc_u32 s13, s13, s17
	s_add_u32 s14, s14, s16
	s_addc_u32 s15, s15, s17
	s_mul_i32 s19, s19, 0x6000
	s_add_u32 s20, s0, s19
	s_addc_u32 s21, s1, 0
	s_add_u32 s20, s20, s18
	s_addc_u32 s21, s21, 0
	global_load_dwordx4 v[244:247], v251, s[20:21]
	global_load_dwordx4 v[160:163], v237, s[12:13]
	global_load_dwordx4 v[164:167], v238, s[12:13]
	global_load_dwordx4 v[168:171], v239, s[12:13]
	global_load_dwordx4 v[172:175], v240, s[12:13]
	global_load_dwordx4 v[196:199], v241, s[12:13]
	global_load_dwordx4 v[200:203], v242, s[12:13]
	global_load_dwordx4 v[204:207], v243, s[12:13]
	global_load_dwordx4 v[184:187], v248, s[12:13]
	ds_write_b32 v249, v112
	ds_write_b32 v249, v113 offset:272
	ds_write_b32 v249, v114 offset:544
	ds_write_b32 v249, v115 offset:816
	ds_write_b32 v249, v116 offset:2176
	ds_write_b32 v249, v117 offset:2448
	ds_write_b32 v249, v118 offset:2720
	ds_write_b32 v249, v119 offset:2992
	ds_write_b32 v249, v120 offset:4352
	ds_write_b32 v249, v121 offset:4624
	ds_write_b32 v249, v122 offset:4896
	ds_write_b32 v249, v123 offset:5168
	ds_write_b32 v249, v124 offset:6528
	ds_write_b32 v249, v125 offset:6800
	ds_write_b32 v249, v126 offset:7072
	ds_write_b32 v249, v127 offset:7344
	ds_write_b32 v249, v96 offset:128
	ds_write_b32 v249, v97 offset:400
	ds_write_b32 v249, v98 offset:672
	ds_write_b32 v249, v99 offset:944
	ds_write_b32 v249, v100 offset:2304
	ds_write_b32 v249, v101 offset:2576
	ds_write_b32 v249, v102 offset:2848
	ds_write_b32 v249, v103 offset:3120
	ds_write_b32 v249, v104 offset:4480
	ds_write_b32 v249, v105 offset:4752
	ds_write_b32 v249, v106 offset:5024
	ds_write_b32 v249, v107 offset:5296
	ds_write_b32 v249, v108 offset:6656
	ds_write_b32 v249, v109 offset:6928
	ds_write_b32 v249, v110 offset:7200
	ds_write_b32 v249, v111 offset:7472
	s_waitcnt lgkmcnt(0)
	ds_read_b128 v[128:131], v250
	ds_read_b128 v[132:135], v250 offset:1088
	ds_read_b128 v[136:139], v250 offset:2176
	ds_read_b128 v[140:143], v250 offset:3264
	ds_read_b128 v[144:147], v250 offset:4352
	ds_read_b128 v[148:151], v250 offset:5440
	ds_read_b128 v[152:155], v250 offset:6528
	ds_read_b128 v[156:159], v250 offset:7616
	s_waitcnt vmcnt(7) lgkmcnt(7)
	v_fma_f32 v128, v244, v128, v160
	v_fma_f32 v129, v245, v129, v161
	v_fma_f32 v130, v246, v130, v162
	v_fma_f32 v131, v247, v131, v163
	global_store_dwordx4 v237, v[128:131], s[14:15]
	s_waitcnt vmcnt(7) lgkmcnt(6)
	v_fma_f32 v132, v244, v132, v164
	v_fma_f32 v133, v245, v133, v165
	v_fma_f32 v134, v246, v134, v166
	v_fma_f32 v135, v247, v135, v167
	global_store_dwordx4 v238, v[132:135], s[14:15]
	s_waitcnt vmcnt(7) lgkmcnt(5)
	v_fma_f32 v136, v244, v136, v168
	v_fma_f32 v137, v245, v137, v169
	v_fma_f32 v138, v246, v138, v170
	v_fma_f32 v139, v247, v139, v171
	global_store_dwordx4 v239, v[136:139], s[14:15]
	s_waitcnt vmcnt(7) lgkmcnt(4)
	v_fma_f32 v140, v244, v140, v172
	v_fma_f32 v141, v245, v141, v173
	v_fma_f32 v142, v246, v142, v174
	v_fma_f32 v143, v247, v143, v175
	global_store_dwordx4 v240, v[140:143], s[14:15]
	s_waitcnt vmcnt(7) lgkmcnt(3)
	v_fma_f32 v144, v244, v144, v196
	v_fma_f32 v145, v245, v145, v197
	v_fma_f32 v146, v246, v146, v198
	v_fma_f32 v147, v247, v147, v199
	global_store_dwordx4 v241, v[144:147], s[14:15]
	s_waitcnt vmcnt(7) lgkmcnt(2)
	v_fma_f32 v148, v244, v148, v200
	v_fma_f32 v149, v245, v149, v201
	v_fma_f32 v150, v246, v150, v202
	v_fma_f32 v151, v247, v151, v203
	global_store_dwordx4 v242, v[148:151], s[14:15]
	s_waitcnt vmcnt(7) lgkmcnt(1)
	v_fma_f32 v152, v244, v152, v204
	v_fma_f32 v153, v245, v153, v205
	v_fma_f32 v154, v246, v154, v206
	v_fma_f32 v155, v247, v155, v207
	global_store_dwordx4 v243, v[152:155], s[14:15]
	s_waitcnt vmcnt(7) lgkmcnt(0)
	v_fma_f32 v156, v244, v156, v184
	v_fma_f32 v157, v245, v157, v185
	v_fma_f32 v158, v246, v158, v186
	v_fma_f32 v159, v247, v159, v187
	global_store_dwordx4 v248, v[156:159], s[14:15]
	global_load_dwordx4 v[244:247], v251, s[20:21] offset:256
	global_load_dwordx4 v[160:163], v237, s[12:13] offset:256
	global_load_dwordx4 v[164:167], v238, s[12:13] offset:256
	global_load_dwordx4 v[168:171], v239, s[12:13] offset:256
	global_load_dwordx4 v[172:175], v240, s[12:13] offset:256
	global_load_dwordx4 v[196:199], v241, s[12:13] offset:256
	global_load_dwordx4 v[200:203], v242, s[12:13] offset:256
	global_load_dwordx4 v[204:207], v243, s[12:13] offset:256
	global_load_dwordx4 v[184:187], v248, s[12:13] offset:256
	ds_write_b32 v249, v80
	ds_write_b32 v249, v81 offset:272
	ds_write_b32 v249, v82 offset:544
	ds_write_b32 v249, v83 offset:816
	ds_write_b32 v249, v84 offset:2176
	ds_write_b32 v249, v85 offset:2448
	ds_write_b32 v249, v86 offset:2720
	ds_write_b32 v249, v87 offset:2992
	ds_write_b32 v249, v88 offset:4352
	ds_write_b32 v249, v89 offset:4624
	ds_write_b32 v249, v90 offset:4896
	ds_write_b32 v249, v91 offset:5168
	ds_write_b32 v249, v92 offset:6528
	ds_write_b32 v249, v93 offset:6800
	ds_write_b32 v249, v94 offset:7072
	ds_write_b32 v249, v95 offset:7344
	ds_write_b32 v249, v64 offset:128
	ds_write_b32 v249, v65 offset:400
	ds_write_b32 v249, v66 offset:672
	ds_write_b32 v249, v67 offset:944
	ds_write_b32 v249, v68 offset:2304
	ds_write_b32 v249, v69 offset:2576
	ds_write_b32 v249, v70 offset:2848
	ds_write_b32 v249, v71 offset:3120
	ds_write_b32 v249, v72 offset:4480
	ds_write_b32 v249, v73 offset:4752
	ds_write_b32 v249, v74 offset:5024
	ds_write_b32 v249, v75 offset:5296
	ds_write_b32 v249, v76 offset:6656
	ds_write_b32 v249, v77 offset:6928
	ds_write_b32 v249, v78 offset:7200
	ds_write_b32 v249, v79 offset:7472
	s_waitcnt lgkmcnt(0)
	ds_read_b128 v[128:131], v250
	ds_read_b128 v[132:135], v250 offset:1088
	ds_read_b128 v[136:139], v250 offset:2176
	ds_read_b128 v[140:143], v250 offset:3264
	ds_read_b128 v[144:147], v250 offset:4352
	ds_read_b128 v[148:151], v250 offset:5440
	ds_read_b128 v[152:155], v250 offset:6528
	ds_read_b128 v[156:159], v250 offset:7616
	s_waitcnt vmcnt(7) lgkmcnt(7)
	v_fma_f32 v128, v244, v128, v160
	v_fma_f32 v129, v245, v129, v161
	v_fma_f32 v130, v246, v130, v162
	v_fma_f32 v131, v247, v131, v163
	global_store_dwordx4 v237, v[128:131], s[14:15] offset:256
	s_waitcnt vmcnt(7) lgkmcnt(6)
	v_fma_f32 v132, v244, v132, v164
	v_fma_f32 v133, v245, v133, v165
	v_fma_f32 v134, v246, v134, v166
	v_fma_f32 v135, v247, v135, v167
	global_store_dwordx4 v238, v[132:135], s[14:15] offset:256
	s_waitcnt vmcnt(7) lgkmcnt(5)
	v_fma_f32 v136, v244, v136, v168
	v_fma_f32 v137, v245, v137, v169
	v_fma_f32 v138, v246, v138, v170
	v_fma_f32 v139, v247, v139, v171
	global_store_dwordx4 v239, v[136:139], s[14:15] offset:256
	s_waitcnt vmcnt(7) lgkmcnt(4)
	v_fma_f32 v140, v244, v140, v172
	v_fma_f32 v141, v245, v141, v173
	v_fma_f32 v142, v246, v142, v174
	v_fma_f32 v143, v247, v143, v175
	global_store_dwordx4 v240, v[140:143], s[14:15] offset:256
	s_waitcnt vmcnt(7) lgkmcnt(3)
	v_fma_f32 v144, v244, v144, v196
	v_fma_f32 v145, v245, v145, v197
	v_fma_f32 v146, v246, v146, v198
	v_fma_f32 v147, v247, v147, v199
	global_store_dwordx4 v241, v[144:147], s[14:15] offset:256
	s_waitcnt vmcnt(7) lgkmcnt(2)
	v_fma_f32 v148, v244, v148, v200
	v_fma_f32 v149, v245, v149, v201
	v_fma_f32 v150, v246, v150, v202
	v_fma_f32 v151, v247, v151, v203
	global_store_dwordx4 v242, v[148:151], s[14:15] offset:256
	s_waitcnt vmcnt(7) lgkmcnt(1)
	v_fma_f32 v152, v244, v152, v204
	v_fma_f32 v153, v245, v153, v205
	v_fma_f32 v154, v246, v154, v206
	v_fma_f32 v155, v247, v155, v207
	global_store_dwordx4 v243, v[152:155], s[14:15] offset:256
	s_waitcnt vmcnt(7) lgkmcnt(0)
	v_fma_f32 v156, v244, v156, v184
	v_fma_f32 v157, v245, v157, v185
	v_fma_f32 v158, v246, v158, v186
	v_fma_f32 v159, v247, v159, v187
	global_store_dwordx4 v248, v[156:159], s[14:15] offset:256
	s_add_u32 s12, s12, 0x20000
	s_addc_u32 s13, s13, 0
	s_add_u32 s14, s14, 0x20000
	s_addc_u32 s15, s15, 0
	global_load_dwordx4 v[244:247], v251, s[20:21]
	global_load_dwordx4 v[160:163], v237, s[12:13]
	global_load_dwordx4 v[164:167], v238, s[12:13]
	global_load_dwordx4 v[168:171], v239, s[12:13]
	global_load_dwordx4 v[172:175], v240, s[12:13]
	global_load_dwordx4 v[196:199], v241, s[12:13]
	global_load_dwordx4 v[200:203], v242, s[12:13]
	global_load_dwordx4 v[204:207], v243, s[12:13]
	global_load_dwordx4 v[184:187], v248, s[12:13]
	ds_write_b32 v249, v48
	ds_write_b32 v249, v49 offset:272
	ds_write_b32 v249, v50 offset:544
	ds_write_b32 v249, v51 offset:816
	ds_write_b32 v249, v52 offset:2176
	ds_write_b32 v249, v53 offset:2448
	ds_write_b32 v249, v54 offset:2720
	ds_write_b32 v249, v55 offset:2992
	ds_write_b32 v249, v56 offset:4352
	ds_write_b32 v249, v57 offset:4624
	ds_write_b32 v249, v58 offset:4896
	ds_write_b32 v249, v59 offset:5168
	ds_write_b32 v249, v60 offset:6528
	ds_write_b32 v249, v61 offset:6800
	ds_write_b32 v249, v62 offset:7072
	ds_write_b32 v249, v63 offset:7344
	ds_write_b32 v249, v32 offset:128
	ds_write_b32 v249, v33 offset:400
	ds_write_b32 v249, v34 offset:672
	ds_write_b32 v249, v35 offset:944
	ds_write_b32 v249, v36 offset:2304
	ds_write_b32 v249, v37 offset:2576
	ds_write_b32 v249, v38 offset:2848
	ds_write_b32 v249, v39 offset:3120
	ds_write_b32 v249, v40 offset:4480
	ds_write_b32 v249, v41 offset:4752
	ds_write_b32 v249, v42 offset:5024
	ds_write_b32 v249, v43 offset:5296
	ds_write_b32 v249, v44 offset:6656
	ds_write_b32 v249, v45 offset:6928
	ds_write_b32 v249, v46 offset:7200
	ds_write_b32 v249, v47 offset:7472
	s_waitcnt lgkmcnt(0)
	ds_read_b128 v[128:131], v250
	ds_read_b128 v[132:135], v250 offset:1088
	ds_read_b128 v[136:139], v250 offset:2176
	ds_read_b128 v[140:143], v250 offset:3264
	ds_read_b128 v[144:147], v250 offset:4352
	ds_read_b128 v[148:151], v250 offset:5440
	ds_read_b128 v[152:155], v250 offset:6528
	ds_read_b128 v[156:159], v250 offset:7616
	s_waitcnt vmcnt(7) lgkmcnt(7)
	v_fma_f32 v128, v244, v128, v160
	v_fma_f32 v129, v245, v129, v161
	v_fma_f32 v130, v246, v130, v162
	v_fma_f32 v131, v247, v131, v163
	global_store_dwordx4 v237, v[128:131], s[14:15]
	s_waitcnt vmcnt(7) lgkmcnt(6)
	v_fma_f32 v132, v244, v132, v164
	v_fma_f32 v133, v245, v133, v165
	v_fma_f32 v134, v246, v134, v166
	v_fma_f32 v135, v247, v135, v167
	global_store_dwordx4 v238, v[132:135], s[14:15]
	s_waitcnt vmcnt(7) lgkmcnt(5)
	v_fma_f32 v136, v244, v136, v168
	v_fma_f32 v137, v245, v137, v169
	v_fma_f32 v138, v246, v138, v170
	v_fma_f32 v139, v247, v139, v171
	global_store_dwordx4 v239, v[136:139], s[14:15]
	s_waitcnt vmcnt(7) lgkmcnt(4)
	v_fma_f32 v140, v244, v140, v172
	v_fma_f32 v141, v245, v141, v173
	v_fma_f32 v142, v246, v142, v174
	v_fma_f32 v143, v247, v143, v175
	global_store_dwordx4 v240, v[140:143], s[14:15]
	s_waitcnt vmcnt(7) lgkmcnt(3)
	v_fma_f32 v144, v244, v144, v196
	v_fma_f32 v145, v245, v145, v197
	v_fma_f32 v146, v246, v146, v198
	v_fma_f32 v147, v247, v147, v199
	global_store_dwordx4 v241, v[144:147], s[14:15]
	s_waitcnt vmcnt(7) lgkmcnt(2)
	v_fma_f32 v148, v244, v148, v200
	v_fma_f32 v149, v245, v149, v201
	v_fma_f32 v150, v246, v150, v202
	v_fma_f32 v151, v247, v151, v203
	global_store_dwordx4 v242, v[148:151], s[14:15]
	s_waitcnt vmcnt(7) lgkmcnt(1)
	v_fma_f32 v152, v244, v152, v204
	v_fma_f32 v153, v245, v153, v205
	v_fma_f32 v154, v246, v154, v206
	v_fma_f32 v155, v247, v155, v207
	global_store_dwordx4 v243, v[152:155], s[14:15]
	s_waitcnt vmcnt(7) lgkmcnt(0)
	v_fma_f32 v156, v244, v156, v184
	v_fma_f32 v157, v245, v157, v185
	v_fma_f32 v158, v246, v158, v186
	v_fma_f32 v159, v247, v159, v187
	global_store_dwordx4 v248, v[156:159], s[14:15]
	global_load_dwordx4 v[244:247], v251, s[20:21] offset:256
	global_load_dwordx4 v[160:163], v237, s[12:13] offset:256
	global_load_dwordx4 v[164:167], v238, s[12:13] offset:256
	global_load_dwordx4 v[168:171], v239, s[12:13] offset:256
	global_load_dwordx4 v[172:175], v240, s[12:13] offset:256
	global_load_dwordx4 v[196:199], v241, s[12:13] offset:256
	global_load_dwordx4 v[200:203], v242, s[12:13] offset:256
	global_load_dwordx4 v[204:207], v243, s[12:13] offset:256
	global_load_dwordx4 v[184:187], v248, s[12:13] offset:256
	ds_write_b32 v249, v16
	ds_write_b32 v249, v17 offset:272
	ds_write_b32 v249, v18 offset:544
	ds_write_b32 v249, v19 offset:816
	ds_write_b32 v249, v20 offset:2176
	ds_write_b32 v249, v21 offset:2448
	ds_write_b32 v249, v22 offset:2720
	ds_write_b32 v249, v23 offset:2992
	ds_write_b32 v249, v24 offset:4352
	ds_write_b32 v249, v25 offset:4624
	ds_write_b32 v249, v26 offset:4896
	ds_write_b32 v249, v27 offset:5168
	ds_write_b32 v249, v28 offset:6528
	ds_write_b32 v249, v29 offset:6800
	ds_write_b32 v249, v30 offset:7072
	ds_write_b32 v249, v31 offset:7344
	ds_write_b32 v249, v0 offset:128
	ds_write_b32 v249, v1 offset:400
	ds_write_b32 v249, v2 offset:672
	ds_write_b32 v249, v3 offset:944
	ds_write_b32 v249, v4 offset:2304
	ds_write_b32 v249, v5 offset:2576
	ds_write_b32 v249, v6 offset:2848
	ds_write_b32 v249, v7 offset:3120
	ds_write_b32 v249, v8 offset:4480
	ds_write_b32 v249, v9 offset:4752
	ds_write_b32 v249, v10 offset:5024
	ds_write_b32 v249, v11 offset:5296
	ds_write_b32 v249, v12 offset:6656
	ds_write_b32 v249, v13 offset:6928
	ds_write_b32 v249, v14 offset:7200
	ds_write_b32 v249, v15 offset:7472
	s_waitcnt lgkmcnt(0)
	ds_read_b128 v[128:131], v250
	ds_read_b128 v[132:135], v250 offset:1088
	ds_read_b128 v[136:139], v250 offset:2176
	ds_read_b128 v[140:143], v250 offset:3264
	ds_read_b128 v[144:147], v250 offset:4352
	ds_read_b128 v[148:151], v250 offset:5440
	ds_read_b128 v[152:155], v250 offset:6528
	ds_read_b128 v[156:159], v250 offset:7616
	s_waitcnt vmcnt(7) lgkmcnt(7)
	v_fma_f32 v128, v244, v128, v160
	v_fma_f32 v129, v245, v129, v161
	v_fma_f32 v130, v246, v130, v162
	v_fma_f32 v131, v247, v131, v163
	global_store_dwordx4 v237, v[128:131], s[14:15] offset:256
	s_waitcnt vmcnt(7) lgkmcnt(6)
	v_fma_f32 v132, v244, v132, v164
	v_fma_f32 v133, v245, v133, v165
	v_fma_f32 v134, v246, v134, v166
	v_fma_f32 v135, v247, v135, v167
	global_store_dwordx4 v238, v[132:135], s[14:15] offset:256
	s_waitcnt vmcnt(7) lgkmcnt(5)
	v_fma_f32 v136, v244, v136, v168
	v_fma_f32 v137, v245, v137, v169
	v_fma_f32 v138, v246, v138, v170
	v_fma_f32 v139, v247, v139, v171
	global_store_dwordx4 v239, v[136:139], s[14:15] offset:256
	s_waitcnt vmcnt(7) lgkmcnt(4)
	v_fma_f32 v140, v244, v140, v172
	v_fma_f32 v141, v245, v141, v173
	v_fma_f32 v142, v246, v142, v174
	v_fma_f32 v143, v247, v143, v175
	global_store_dwordx4 v240, v[140:143], s[14:15] offset:256
	s_waitcnt vmcnt(7) lgkmcnt(3)
	v_fma_f32 v144, v244, v144, v196
	v_fma_f32 v145, v245, v145, v197
	v_fma_f32 v146, v246, v146, v198
	v_fma_f32 v147, v247, v147, v199
	global_store_dwordx4 v241, v[144:147], s[14:15] offset:256
	s_waitcnt vmcnt(7) lgkmcnt(2)
	v_fma_f32 v148, v244, v148, v200
	v_fma_f32 v149, v245, v149, v201
	v_fma_f32 v150, v246, v150, v202
	v_fma_f32 v151, v247, v151, v203
	global_store_dwordx4 v242, v[148:151], s[14:15] offset:256
	s_waitcnt vmcnt(7) lgkmcnt(1)
	v_fma_f32 v152, v244, v152, v204
	v_fma_f32 v153, v245, v153, v205
	v_fma_f32 v154, v246, v154, v206
	v_fma_f32 v155, v247, v155, v207
	global_store_dwordx4 v243, v[152:155], s[14:15] offset:256
	s_waitcnt vmcnt(7) lgkmcnt(0)
	v_fma_f32 v156, v244, v156, v184
	v_fma_f32 v157, v245, v157, v185
	v_fma_f32 v158, v246, v158, v186
	v_fma_f32 v159, v247, v159, v187
	global_store_dwordx4 v248, v[156:159], s[14:15] offset:256
	s_waitcnt lgkmcnt(0)
	v_readlane_b32 s16, v254, 11
	s_andn2_b32 s17, s26, 63
	s_add_i32 s2, s2, s16
	s_cmp_lt_i32 s2, s17
	s_cbranch_scc0 .Lhx_down_left
	s_barrier
	s_branch .LBB0_1086
.Lhx_down_left:
	s_and_b32 s18, s26, 63
	s_cbranch_scc0 .Lhx_down_done
	v_readlane_b32 s19, v253, 0
	s_lshl_b32 s18, s18, 1
	s_ashr_i32 s19, s19, 3
	s_cmp_lt_i32 s19, s18
	s_cbranch_scc0 .Lhx_down_done
	s_mov_b32 s100, 1
	s_and_b32 s101, s19, 1
	s_lshr_b32 s19, s19, 1
	s_add_i32 s2, s17, s19
	s_barrier
	s_branch .LBB0_1086
.Lhx_down_done:
	s_barrier
	s_branch .LBB0_1089
.Lhx_down_half:
	v_bfe_u32 v247, v181, 4, 2
	v_lshlrev_b32_e32 v247, 1, v247
	v_mov_b32_e32 v176, 0x78
	v_lshrrev_b32_e32 v247, v247, v176
	v_and_b32_e32 v247, 3, v247
	v_and_b32_e32 v246, 3, v181
	v_xor_b32_e32 v247, v247, v246
	v_lshlrev_b32_e32 v247, 4, v247
	v_and_b32_e32 v188, 0xffffffcf, v186
	v_or_b32_e32 v188, v188, v247
	v_mov_b32_e32 v189, v187
	v_lshrrev_b32_e32 v176, 6, v181
	v_lshlrev_b32_e32 v247, 11, v176
	v_lshlrev_b32_e32 v176, 10, v176
	v_lshl_add_u64 v[188:189], v[188:189], 0, v[176:177]
	v_readfirstlane_b32 vcc_lo, v247
	v_bfe_u32 v247, v181, 4, 1
	v_lshlrev_b32_e32 v176, 9, v183
	v_lshl_add_u32 v176, v247, 8, v176
	v_lshl_add_u64 v[184:185], v[184:185], 0, v[176:177]
	v_mov_b32_e32 v176, s24
	v_lshl_add_u64 v[186:187], v[184:185], 0, v[176:177]
	v_mov_b32_e32 v176, 0x78
	v_bfe_u32 v247, v181, 2, 2
	v_lshlrev_b32_e32 v247, 1, v247
	v_lshrrev_b32_e32 v247, v247, v176
	v_and_b32_e32 v247, 3, v247
	v_bfe_u32 v246, v181, 4, 2
	v_xor_b32_e32 v247, v247, v246
	v_lshlrev_b32_e32 v247, 4, v247
	v_and_b32_e32 v246, 15, v181
	v_lshl_add_u32 v246, v246, 6, v247
	s_cmp_eq_u32 s101, 1
	s_cbranch_scc0 .Lg16_downh_a0
	v_mov_b32_e32 v184, v186
	v_mov_b32_e32 v185, v187
.Lg16_downh_a0:
	s_mov_b32 s96, 0
	s_mov_b32 m0, vcc_lo
	v_lshl_add_u64 v[160:161], v[188:189], 0, s[96:97]
	global_load_lds_dwordx4 v[160:161], off
	global_load_lds_dwordx4 v[160:161], off offset:1024
	s_mov_b32 s96, 0
	v_lshl_add_u64 v[248:249], v[184:185], 0, s[96:97]
	v_lshl_add_u64 v[250:251], v[186:187], 0, s[96:97]
	global_load_dwordx4 v[128:131], v[248:249], off
	global_load_dwordx4 v[132:135], v[248:249], off offset:256
	s_movk_i32 s96, 0x2000
	s_add_i32 m0, vcc_lo, 8192
	v_lshl_add_u64 v[160:161], v[188:189], 0, s[96:97]
	global_load_lds_dwordx4 v[160:161], off
	global_load_lds_dwordx4 v[160:161], off offset:1024
	s_movk_i32 s96, 0x800
	v_lshl_add_u64 v[248:249], v[184:185], 0, s[96:97]
	v_lshl_add_u64 v[250:251], v[186:187], 0, s[96:97]
	global_load_dwordx4 v[144:147], v[248:249], off
	global_load_dwordx4 v[148:151], v[248:249], off offset:256
	v_mov_b32_e32 v0, 0
	v_mov_b32_e32 v1, 0
	v_mov_b32_e32 v2, 0
	v_mov_b32_e32 v3, 0
	v_mov_b32_e32 v4, 0
	v_mov_b32_e32 v5, 0
	v_mov_b32_e32 v6, 0
	v_mov_b32_e32 v7, 0
	v_mov_b32_e32 v8, 0
	v_mov_b32_e32 v9, 0
	v_mov_b32_e32 v10, 0
	v_mov_b32_e32 v11, 0
	v_mov_b32_e32 v12, 0
	v_mov_b32_e32 v13, 0
	v_mov_b32_e32 v14, 0
	v_mov_b32_e32 v15, 0
	v_mov_b32_e32 v16, 0
	v_mov_b32_e32 v17, 0
	v_mov_b32_e32 v18, 0
	v_mov_b32_e32 v19, 0
	v_mov_b32_e32 v20, 0
	v_mov_b32_e32 v21, 0
	v_mov_b32_e32 v22, 0
	v_mov_b32_e32 v23, 0
	v_mov_b32_e32 v24, 0
	v_mov_b32_e32 v25, 0
	v_mov_b32_e32 v26, 0
	v_mov_b32_e32 v27, 0
	v_mov_b32_e32 v28, 0
	v_mov_b32_e32 v29, 0
	v_mov_b32_e32 v30, 0
	v_mov_b32_e32 v31, 0
	v_mov_b32_e32 v32, 0
	v_mov_b32_e32 v33, 0
	v_mov_b32_e32 v34, 0
	v_mov_b32_e32 v35, 0
	v_mov_b32_e32 v36, 0
	v_mov_b32_e32 v37, 0
	v_mov_b32_e32 v38, 0
	v_mov_b32_e32 v39, 0
	v_mov_b32_e32 v40, 0
	v_mov_b32_e32 v41, 0
	v_mov_b32_e32 v42, 0
	v_mov_b32_e32 v43, 0
	v_mov_b32_e32 v44, 0
	v_mov_b32_e32 v45, 0
	v_mov_b32_e32 v46, 0
	v_mov_b32_e32 v47, 0
	v_mov_b32_e32 v48, 0
	v_mov_b32_e32 v49, 0
	v_mov_b32_e32 v50, 0
	v_mov_b32_e32 v51, 0
	v_mov_b32_e32 v52, 0
	v_mov_b32_e32 v53, 0
	v_mov_b32_e32 v54, 0
	v_mov_b32_e32 v55, 0
	v_mov_b32_e32 v56, 0
	v_mov_b32_e32 v57, 0
	v_mov_b32_e32 v58, 0
	v_mov_b32_e32 v59, 0
	v_mov_b32_e32 v60, 0
	v_mov_b32_e32 v61, 0
	v_mov_b32_e32 v62, 0
	v_mov_b32_e32 v63, 0
	v_mov_b32_e32 v64, 0
	v_mov_b32_e32 v65, 0
	v_mov_b32_e32 v66, 0
	v_mov_b32_e32 v67, 0
	v_mov_b32_e32 v68, 0
	v_mov_b32_e32 v69, 0
	v_mov_b32_e32 v70, 0
	v_mov_b32_e32 v71, 0
	v_mov_b32_e32 v72, 0
	v_mov_b32_e32 v73, 0
	v_mov_b32_e32 v74, 0
	v_mov_b32_e32 v75, 0
	v_mov_b32_e32 v76, 0
	v_mov_b32_e32 v77, 0
	v_mov_b32_e32 v78, 0
	v_mov_b32_e32 v79, 0
	v_mov_b32_e32 v80, 0
	v_mov_b32_e32 v81, 0
	v_mov_b32_e32 v82, 0
	v_mov_b32_e32 v83, 0
	v_mov_b32_e32 v84, 0
	v_mov_b32_e32 v85, 0
	v_mov_b32_e32 v86, 0
	v_mov_b32_e32 v87, 0
	v_mov_b32_e32 v88, 0
	v_mov_b32_e32 v89, 0
	v_mov_b32_e32 v90, 0
	v_mov_b32_e32 v91, 0
	v_mov_b32_e32 v92, 0
	v_mov_b32_e32 v93, 0
	v_mov_b32_e32 v94, 0
	v_mov_b32_e32 v95, 0
	v_mov_b32_e32 v96, 0
	v_mov_b32_e32 v97, 0
	v_mov_b32_e32 v98, 0
	v_mov_b32_e32 v99, 0
	v_mov_b32_e32 v100, 0
	v_mov_b32_e32 v101, 0
	v_mov_b32_e32 v102, 0
	v_mov_b32_e32 v103, 0
	v_mov_b32_e32 v104, 0
	v_mov_b32_e32 v105, 0
	v_mov_b32_e32 v106, 0
	v_mov_b32_e32 v107, 0
	v_mov_b32_e32 v108, 0
	v_mov_b32_e32 v109, 0
	v_mov_b32_e32 v110, 0
	v_mov_b32_e32 v111, 0
	v_mov_b32_e32 v112, 0
	v_mov_b32_e32 v113, 0
	v_mov_b32_e32 v114, 0
	v_mov_b32_e32 v115, 0
	v_mov_b32_e32 v116, 0
	v_mov_b32_e32 v117, 0
	v_mov_b32_e32 v118, 0
	v_mov_b32_e32 v119, 0
	v_mov_b32_e32 v120, 0
	v_mov_b32_e32 v121, 0
	v_mov_b32_e32 v122, 0
	v_mov_b32_e32 v123, 0
	v_mov_b32_e32 v124, 0
	v_mov_b32_e32 v125, 0
	v_mov_b32_e32 v126, 0
	v_mov_b32_e32 v127, 0
	s_mov_b32 s8, 0
	s_waitcnt vmcnt(2)
	s_barrier
.Lg16_downh_k:
	s_add_i32 s9, s8, 2
	s_lshl_b32 s96, s9, 13
	s_add_i32 m0, vcc_lo, 16384
	v_lshl_add_u64 v[160:161], v[188:189], 0, s[96:97]
	global_load_lds_dwordx4 v[160:161], off
	global_load_lds_dwordx4 v[160:161], off offset:1024
	ds_read_b128 v[196:199], v246 offset:0
	ds_read_b128 v[200:203], v246 offset:1024
	ds_read_b128 v[204:207], v246 offset:2048
	ds_read_b128 v[242:245], v246 offset:3072
	s_add_i32 s9, s8, 2
	s_lshl_b32 s96, s9, 11
	v_lshl_add_u64 v[248:249], v[184:185], 0, s[96:97]
	v_lshl_add_u64 v[250:251], v[186:187], 0, s[96:97]
	s_waitcnt vmcnt(6) lgkmcnt(3)
	v_mfma_f32_16x16x32_bf16 v[112:115], v[128:131], v[196:199], v[112:115]
	v_mfma_f32_16x16x32_bf16 v[120:123], v[132:135], v[196:199], v[120:123]
	ds_read_b128 v[196:199], v246 offset:4096
	s_waitcnt lgkmcnt(3)
	v_mfma_f32_16x16x32_bf16 v[116:119], v[128:131], v[200:203], v[116:119]
	v_mfma_f32_16x16x32_bf16 v[124:127], v[132:135], v[200:203], v[124:127]
	ds_read_b128 v[200:203], v246 offset:5120
	s_waitcnt lgkmcnt(3)
	v_mfma_f32_16x16x32_bf16 v[96:99], v[128:131], v[204:207], v[96:99]
	v_mfma_f32_16x16x32_bf16 v[104:107], v[132:135], v[204:207], v[104:107]
	ds_read_b128 v[204:207], v246 offset:6144
	s_waitcnt lgkmcnt(3)
	v_mfma_f32_16x16x32_bf16 v[100:103], v[128:131], v[242:245], v[100:103]
	v_mfma_f32_16x16x32_bf16 v[108:111], v[132:135], v[242:245], v[108:111]
	ds_read_b128 v[242:245], v246 offset:7168
	s_waitcnt lgkmcnt(3)
	v_mfma_f32_16x16x32_bf16 v[80:83], v[128:131], v[196:199], v[80:83]
	v_mfma_f32_16x16x32_bf16 v[88:91], v[132:135], v[196:199], v[88:91]
	s_waitcnt lgkmcnt(2)
	v_mfma_f32_16x16x32_bf16 v[84:87], v[128:131], v[200:203], v[84:87]
	v_mfma_f32_16x16x32_bf16 v[92:95], v[132:135], v[200:203], v[92:95]
	s_waitcnt lgkmcnt(1)
	v_mfma_f32_16x16x32_bf16 v[64:67], v[128:131], v[204:207], v[64:67]
	v_mfma_f32_16x16x32_bf16 v[72:75], v[132:135], v[204:207], v[72:75]
	s_waitcnt lgkmcnt(0)
	v_mfma_f32_16x16x32_bf16 v[68:71], v[128:131], v[242:245], v[68:71]
	v_mfma_f32_16x16x32_bf16 v[76:79], v[132:135], v[242:245], v[76:79]
	global_load_dwordx4 v[128:131], v[248:249], off
	global_load_dwordx4 v[132:135], v[248:249], off offset:256
	s_waitcnt vmcnt(6)
	s_barrier
	s_add_i32 s9, s8, 3
	s_lshl_b32 s96, s9, 13
	s_mov_b32 m0, vcc_lo
	v_lshl_add_u64 v[160:161], v[188:189], 0, s[96:97]
	global_load_lds_dwordx4 v[160:161], off
	global_load_lds_dwordx4 v[160:161], off offset:1024
	ds_read_b128 v[196:199], v246 offset:8192
	ds_read_b128 v[200:203], v246 offset:9216
	ds_read_b128 v[204:207], v246 offset:10240
	ds_read_b128 v[242:245], v246 offset:11264
	s_add_i32 s9, s8, 3
	s_lshl_b32 s96, s9, 11
	v_lshl_add_u64 v[248:249], v[184:185], 0, s[96:97]
	v_lshl_add_u64 v[250:251], v[186:187], 0, s[96:97]
	s_waitcnt vmcnt(6) lgkmcnt(3)
	v_mfma_f32_16x16x32_bf16 v[112:115], v[144:147], v[196:199], v[112:115]
	v_mfma_f32_16x16x32_bf16 v[120:123], v[148:151], v[196:199], v[120:123]
	ds_read_b128 v[196:199], v246 offset:12288
	s_waitcnt lgkmcnt(3)
	v_mfma_f32_16x16x32_bf16 v[116:119], v[144:147], v[200:203], v[116:119]
	v_mfma_f32_16x16x32_bf16 v[124:127], v[148:151], v[200:203], v[124:127]
	ds_read_b128 v[200:203], v246 offset:13312
	s_waitcnt lgkmcnt(3)
	v_mfma_f32_16x16x32_bf16 v[96:99], v[144:147], v[204:207], v[96:99]
	v_mfma_f32_16x16x32_bf16 v[104:107], v[148:151], v[204:207], v[104:107]
	ds_read_b128 v[204:207], v246 offset:14336
	s_waitcnt lgkmcnt(3)
	v_mfma_f32_16x16x32_bf16 v[100:103], v[144:147], v[242:245], v[100:103]
	v_mfma_f32_16x16x32_bf16 v[108:111], v[148:151], v[242:245], v[108:111]
	ds_read_b128 v[242:245], v246 offset:15360
	s_waitcnt lgkmcnt(3)
	v_mfma_f32_16x16x32_bf16 v[80:83], v[144:147], v[196:199], v[80:83]
	v_mfma_f32_16x16x32_bf16 v[88:91], v[148:151], v[196:199], v[88:91]
	s_waitcnt lgkmcnt(2)
	v_mfma_f32_16x16x32_bf16 v[84:87], v[144:147], v[200:203], v[84:87]
	v_mfma_f32_16x16x32_bf16 v[92:95], v[148:151], v[200:203], v[92:95]
	s_waitcnt lgkmcnt(1)
	v_mfma_f32_16x16x32_bf16 v[64:67], v[144:147], v[204:207], v[64:67]
	v_mfma_f32_16x16x32_bf16 v[72:75], v[148:151], v[204:207], v[72:75]
	s_waitcnt lgkmcnt(0)
	v_mfma_f32_16x16x32_bf16 v[68:71], v[144:147], v[242:245], v[68:71]
	v_mfma_f32_16x16x32_bf16 v[76:79], v[148:151], v[242:245], v[76:79]
	global_load_dwordx4 v[144:147], v[248:249], off
	global_load_dwordx4 v[148:151], v[248:249], off offset:256
	s_waitcnt vmcnt(6)
	s_barrier
	s_add_i32 s9, s8, 4
	s_lshl_b32 s96, s9, 13
	s_add_i32 m0, vcc_lo, 8192
	v_lshl_add_u64 v[160:161], v[188:189], 0, s[96:97]
	global_load_lds_dwordx4 v[160:161], off
	global_load_lds_dwordx4 v[160:161], off offset:1024
	ds_read_b128 v[196:199], v246 offset:16384
	ds_read_b128 v[200:203], v246 offset:17408
	ds_read_b128 v[204:207], v246 offset:18432
	ds_read_b128 v[242:245], v246 offset:19456
	s_add_i32 s9, s8, 4
	s_lshl_b32 s96, s9, 11
	v_lshl_add_u64 v[248:249], v[184:185], 0, s[96:97]
	v_lshl_add_u64 v[250:251], v[186:187], 0, s[96:97]
	s_waitcnt vmcnt(6) lgkmcnt(3)
	v_mfma_f32_16x16x32_bf16 v[112:115], v[128:131], v[196:199], v[112:115]
	v_mfma_f32_16x16x32_bf16 v[120:123], v[132:135], v[196:199], v[120:123]
	ds_read_b128 v[196:199], v246 offset:20480
	s_waitcnt lgkmcnt(3)
	v_mfma_f32_16x16x32_bf16 v[116:119], v[128:131], v[200:203], v[116:119]
	v_mfma_f32_16x16x32_bf16 v[124:127], v[132:135], v[200:203], v[124:127]
	ds_read_b128 v[200:203], v246 offset:21504
	s_waitcnt lgkmcnt(3)
	v_mfma_f32_16x16x32_bf16 v[96:99], v[128:131], v[204:207], v[96:99]
	v_mfma_f32_16x16x32_bf16 v[104:107], v[132:135], v[204:207], v[104:107]
	ds_read_b128 v[204:207], v246 offset:22528
	s_waitcnt lgkmcnt(3)
	v_mfma_f32_16x16x32_bf16 v[100:103], v[128:131], v[242:245], v[100:103]
	v_mfma_f32_16x16x32_bf16 v[108:111], v[132:135], v[242:245], v[108:111]
	ds_read_b128 v[242:245], v246 offset:23552
	s_waitcnt lgkmcnt(3)
	v_mfma_f32_16x16x32_bf16 v[80:83], v[128:131], v[196:199], v[80:83]
	v_mfma_f32_16x16x32_bf16 v[88:91], v[132:135], v[196:199], v[88:91]
	s_waitcnt lgkmcnt(2)
	v_mfma_f32_16x16x32_bf16 v[84:87], v[128:131], v[200:203], v[84:87]
	v_mfma_f32_16x16x32_bf16 v[92:95], v[132:135], v[200:203], v[92:95]
	s_waitcnt lgkmcnt(1)
	v_mfma_f32_16x16x32_bf16 v[64:67], v[128:131], v[204:207], v[64:67]
	v_mfma_f32_16x16x32_bf16 v[72:75], v[132:135], v[204:207], v[72:75]
	s_waitcnt lgkmcnt(0)
	v_mfma_f32_16x16x32_bf16 v[68:71], v[128:131], v[242:245], v[68:71]
	v_mfma_f32_16x16x32_bf16 v[76:79], v[132:135], v[242:245], v[76:79]
	global_load_dwordx4 v[128:131], v[248:249], off
	global_load_dwordx4 v[132:135], v[248:249], off offset:256
	s_waitcnt vmcnt(6)
	s_barrier
	s_add_i32 s9, s8, 5
	s_lshl_b32 s96, s9, 13
	s_add_i32 m0, vcc_lo, 16384
	v_lshl_add_u64 v[160:161], v[188:189], 0, s[96:97]
	global_load_lds_dwordx4 v[160:161], off
	global_load_lds_dwordx4 v[160:161], off offset:1024
	ds_read_b128 v[196:199], v246 offset:0
	ds_read_b128 v[200:203], v246 offset:1024
	ds_read_b128 v[204:207], v246 offset:2048
	ds_read_b128 v[242:245], v246 offset:3072
	s_add_i32 s9, s8, 5
	s_lshl_b32 s96, s9, 11
	v_lshl_add_u64 v[248:249], v[184:185], 0, s[96:97]
	v_lshl_add_u64 v[250:251], v[186:187], 0, s[96:97]
	s_waitcnt vmcnt(6) lgkmcnt(3)
	v_mfma_f32_16x16x32_bf16 v[112:115], v[144:147], v[196:199], v[112:115]
	v_mfma_f32_16x16x32_bf16 v[120:123], v[148:151], v[196:199], v[120:123]
	ds_read_b128 v[196:199], v246 offset:4096
	s_waitcnt lgkmcnt(3)
	v_mfma_f32_16x16x32_bf16 v[116:119], v[144:147], v[200:203], v[116:119]
	v_mfma_f32_16x16x32_bf16 v[124:127], v[148:151], v[200:203], v[124:127]
	ds_read_b128 v[200:203], v246 offset:5120
	s_waitcnt lgkmcnt(3)
	v_mfma_f32_16x16x32_bf16 v[96:99], v[144:147], v[204:207], v[96:99]
	v_mfma_f32_16x16x32_bf16 v[104:107], v[148:151], v[204:207], v[104:107]
	ds_read_b128 v[204:207], v246 offset:6144
	s_waitcnt lgkmcnt(3)
	v_mfma_f32_16x16x32_bf16 v[100:103], v[144:147], v[242:245], v[100:103]
	v_mfma_f32_16x16x32_bf16 v[108:111], v[148:151], v[242:245], v[108:111]
	ds_read_b128 v[242:245], v246 offset:7168
	s_waitcnt lgkmcnt(3)
	v_mfma_f32_16x16x32_bf16 v[80:83], v[144:147], v[196:199], v[80:83]
	v_mfma_f32_16x16x32_bf16 v[88:91], v[148:151], v[196:199], v[88:91]
	s_waitcnt lgkmcnt(2)
	v_mfma_f32_16x16x32_bf16 v[84:87], v[144:147], v[200:203], v[84:87]
	v_mfma_f32_16x16x32_bf16 v[92:95], v[148:151], v[200:203], v[92:95]
	s_waitcnt lgkmcnt(1)
	v_mfma_f32_16x16x32_bf16 v[64:67], v[144:147], v[204:207], v[64:67]
	v_mfma_f32_16x16x32_bf16 v[72:75], v[148:151], v[204:207], v[72:75]
	s_waitcnt lgkmcnt(0)
	v_mfma_f32_16x16x32_bf16 v[68:71], v[144:147], v[242:245], v[68:71]
	v_mfma_f32_16x16x32_bf16 v[76:79], v[148:151], v[242:245], v[76:79]
	global_load_dwordx4 v[144:147], v[248:249], off
	global_load_dwordx4 v[148:151], v[248:249], off offset:256
	s_waitcnt vmcnt(6)
	s_barrier
	s_add_i32 s9, s8, 6
	s_lshl_b32 s96, s9, 13
	s_mov_b32 m0, vcc_lo
	v_lshl_add_u64 v[160:161], v[188:189], 0, s[96:97]
	global_load_lds_dwordx4 v[160:161], off
	global_load_lds_dwordx4 v[160:161], off offset:1024
	ds_read_b128 v[196:199], v246 offset:8192
	ds_read_b128 v[200:203], v246 offset:9216
	ds_read_b128 v[204:207], v246 offset:10240
	ds_read_b128 v[242:245], v246 offset:11264
	s_add_i32 s9, s8, 6
	s_lshl_b32 s96, s9, 11
	v_lshl_add_u64 v[248:249], v[184:185], 0, s[96:97]
	v_lshl_add_u64 v[250:251], v[186:187], 0, s[96:97]
	s_waitcnt vmcnt(6) lgkmcnt(3)
	v_mfma_f32_16x16x32_bf16 v[112:115], v[128:131], v[196:199], v[112:115]
	v_mfma_f32_16x16x32_bf16 v[120:123], v[132:135], v[196:199], v[120:123]
	ds_read_b128 v[196:199], v246 offset:12288
	s_waitcnt lgkmcnt(3)
	v_mfma_f32_16x16x32_bf16 v[116:119], v[128:131], v[200:203], v[116:119]
	v_mfma_f32_16x16x32_bf16 v[124:127], v[132:135], v[200:203], v[124:127]
	ds_read_b128 v[200:203], v246 offset:13312
	s_waitcnt lgkmcnt(3)
	v_mfma_f32_16x16x32_bf16 v[96:99], v[128:131], v[204:207], v[96:99]
	v_mfma_f32_16x16x32_bf16 v[104:107], v[132:135], v[204:207], v[104:107]
	ds_read_b128 v[204:207], v246 offset:14336
	s_waitcnt lgkmcnt(3)
	v_mfma_f32_16x16x32_bf16 v[100:103], v[128:131], v[242:245], v[100:103]
	v_mfma_f32_16x16x32_bf16 v[108:111], v[132:135], v[242:245], v[108:111]
	ds_read_b128 v[242:245], v246 offset:15360
	s_waitcnt lgkmcnt(3)
	v_mfma_f32_16x16x32_bf16 v[80:83], v[128:131], v[196:199], v[80:83]
	v_mfma_f32_16x16x32_bf16 v[88:91], v[132:135], v[196:199], v[88:91]
	s_waitcnt lgkmcnt(2)
	v_mfma_f32_16x16x32_bf16 v[84:87], v[128:131], v[200:203], v[84:87]
	v_mfma_f32_16x16x32_bf16 v[92:95], v[132:135], v[200:203], v[92:95]
	s_waitcnt lgkmcnt(1)
	v_mfma_f32_16x16x32_bf16 v[64:67], v[128:131], v[204:207], v[64:67]
	v_mfma_f32_16x16x32_bf16 v[72:75], v[132:135], v[204:207], v[72:75]
	s_waitcnt lgkmcnt(0)
	v_mfma_f32_16x16x32_bf16 v[68:71], v[128:131], v[242:245], v[68:71]
	v_mfma_f32_16x16x32_bf16 v[76:79], v[132:135], v[242:245], v[76:79]
	global_load_dwordx4 v[128:131], v[248:249], off
	global_load_dwordx4 v[132:135], v[248:249], off offset:256
	s_waitcnt vmcnt(6)
	s_barrier
	s_add_i32 s9, s8, 7
	s_lshl_b32 s96, s9, 13
	s_add_i32 m0, vcc_lo, 8192
	v_lshl_add_u64 v[160:161], v[188:189], 0, s[96:97]
	global_load_lds_dwordx4 v[160:161], off
	global_load_lds_dwordx4 v[160:161], off offset:1024
	ds_read_b128 v[196:199], v246 offset:16384
	ds_read_b128 v[200:203], v246 offset:17408
	ds_read_b128 v[204:207], v246 offset:18432
	ds_read_b128 v[242:245], v246 offset:19456
	s_add_i32 s9, s8, 7
	s_lshl_b32 s96, s9, 11
	v_lshl_add_u64 v[248:249], v[184:185], 0, s[96:97]
	v_lshl_add_u64 v[250:251], v[186:187], 0, s[96:97]
	s_waitcnt vmcnt(6) lgkmcnt(3)
	v_mfma_f32_16x16x32_bf16 v[112:115], v[144:147], v[196:199], v[112:115]
	v_mfma_f32_16x16x32_bf16 v[120:123], v[148:151], v[196:199], v[120:123]
	ds_read_b128 v[196:199], v246 offset:20480
	s_waitcnt lgkmcnt(3)
	v_mfma_f32_16x16x32_bf16 v[116:119], v[144:147], v[200:203], v[116:119]
	v_mfma_f32_16x16x32_bf16 v[124:127], v[148:151], v[200:203], v[124:127]
	ds_read_b128 v[200:203], v246 offset:21504
	s_waitcnt lgkmcnt(3)
	v_mfma_f32_16x16x32_bf16 v[96:99], v[144:147], v[204:207], v[96:99]
	v_mfma_f32_16x16x32_bf16 v[104:107], v[148:151], v[204:207], v[104:107]
	ds_read_b128 v[204:207], v246 offset:22528
	s_waitcnt lgkmcnt(3)
	v_mfma_f32_16x16x32_bf16 v[100:103], v[144:147], v[242:245], v[100:103]
	v_mfma_f32_16x16x32_bf16 v[108:111], v[148:151], v[242:245], v[108:111]
	ds_read_b128 v[242:245], v246 offset:23552
	s_waitcnt lgkmcnt(3)
	v_mfma_f32_16x16x32_bf16 v[80:83], v[144:147], v[196:199], v[80:83]
	v_mfma_f32_16x16x32_bf16 v[88:91], v[148:151], v[196:199], v[88:91]
	s_waitcnt lgkmcnt(2)
	v_mfma_f32_16x16x32_bf16 v[84:87], v[144:147], v[200:203], v[84:87]
	v_mfma_f32_16x16x32_bf16 v[92:95], v[148:151], v[200:203], v[92:95]
	s_waitcnt lgkmcnt(1)
	v_mfma_f32_16x16x32_bf16 v[64:67], v[144:147], v[204:207], v[64:67]
	v_mfma_f32_16x16x32_bf16 v[72:75], v[148:151], v[204:207], v[72:75]
	s_waitcnt lgkmcnt(0)
	v_mfma_f32_16x16x32_bf16 v[68:71], v[144:147], v[242:245], v[68:71]
	v_mfma_f32_16x16x32_bf16 v[76:79], v[148:151], v[242:245], v[76:79]
	global_load_dwordx4 v[144:147], v[248:249], off
	global_load_dwordx4 v[148:151], v[248:249], off offset:256
	s_waitcnt vmcnt(6)
	s_barrier
	s_add_i32 s8, s8, 6
	s_cmp_lt_u32 s8, 84
	s_cbranch_scc1 .Lg16_downh_k
	s_mov_b32 s96, 0xac000
	s_add_i32 m0, vcc_lo, 16384
	v_lshl_add_u64 v[160:161], v[188:189], 0, s[96:97]
	global_load_lds_dwordx4 v[160:161], off
	global_load_lds_dwordx4 v[160:161], off offset:1024
	ds_read_b128 v[196:199], v246 offset:0
	ds_read_b128 v[200:203], v246 offset:1024
	ds_read_b128 v[204:207], v246 offset:2048
	ds_read_b128 v[242:245], v246 offset:3072
	s_mov_b32 s96, 0x2b000
	v_lshl_add_u64 v[248:249], v[184:185], 0, s[96:97]
	v_lshl_add_u64 v[250:251], v[186:187], 0, s[96:97]
	s_waitcnt vmcnt(6) lgkmcnt(3)
	v_mfma_f32_16x16x32_bf16 v[112:115], v[128:131], v[196:199], v[112:115]
	v_mfma_f32_16x16x32_bf16 v[120:123], v[132:135], v[196:199], v[120:123]
	ds_read_b128 v[196:199], v246 offset:4096
	s_waitcnt lgkmcnt(3)
	v_mfma_f32_16x16x32_bf16 v[116:119], v[128:131], v[200:203], v[116:119]
	v_mfma_f32_16x16x32_bf16 v[124:127], v[132:135], v[200:203], v[124:127]
	ds_read_b128 v[200:203], v246 offset:5120
	s_waitcnt lgkmcnt(3)
	v_mfma_f32_16x16x32_bf16 v[96:99], v[128:131], v[204:207], v[96:99]
	v_mfma_f32_16x16x32_bf16 v[104:107], v[132:135], v[204:207], v[104:107]
	ds_read_b128 v[204:207], v246 offset:6144
	s_waitcnt lgkmcnt(3)
	v_mfma_f32_16x16x32_bf16 v[100:103], v[128:131], v[242:245], v[100:103]
	v_mfma_f32_16x16x32_bf16 v[108:111], v[132:135], v[242:245], v[108:111]
	ds_read_b128 v[242:245], v246 offset:7168
	s_waitcnt lgkmcnt(3)
	v_mfma_f32_16x16x32_bf16 v[80:83], v[128:131], v[196:199], v[80:83]
	v_mfma_f32_16x16x32_bf16 v[88:91], v[132:135], v[196:199], v[88:91]
	s_waitcnt lgkmcnt(2)
	v_mfma_f32_16x16x32_bf16 v[84:87], v[128:131], v[200:203], v[84:87]
	v_mfma_f32_16x16x32_bf16 v[92:95], v[132:135], v[200:203], v[92:95]
	s_waitcnt lgkmcnt(1)
	v_mfma_f32_16x16x32_bf16 v[64:67], v[128:131], v[204:207], v[64:67]
	v_mfma_f32_16x16x32_bf16 v[72:75], v[132:135], v[204:207], v[72:75]
	s_waitcnt lgkmcnt(0)
	v_mfma_f32_16x16x32_bf16 v[68:71], v[128:131], v[242:245], v[68:71]
	v_mfma_f32_16x16x32_bf16 v[76:79], v[132:135], v[242:245], v[76:79]
	global_load_dwordx4 v[128:131], v[248:249], off
	global_load_dwordx4 v[132:135], v[248:249], off offset:256
	s_waitcnt vmcnt(6)
	s_barrier
	s_mov_b32 s96, 0xae000
	s_mov_b32 m0, vcc_lo
	v_lshl_add_u64 v[160:161], v[188:189], 0, s[96:97]
	global_load_lds_dwordx4 v[160:161], off
	global_load_lds_dwordx4 v[160:161], off offset:1024
	ds_read_b128 v[196:199], v246 offset:8192
	ds_read_b128 v[200:203], v246 offset:9216
	ds_read_b128 v[204:207], v246 offset:10240
	ds_read_b128 v[242:245], v246 offset:11264
	s_mov_b32 s96, 0x2b800
	v_lshl_add_u64 v[248:249], v[184:185], 0, s[96:97]
	v_lshl_add_u64 v[250:251], v[186:187], 0, s[96:97]
	s_waitcnt vmcnt(6) lgkmcnt(3)
	v_mfma_f32_16x16x32_bf16 v[112:115], v[144:147], v[196:199], v[112:115]
	v_mfma_f32_16x16x32_bf16 v[120:123], v[148:151], v[196:199], v[120:123]
	ds_read_b128 v[196:199], v246 offset:12288
	s_waitcnt lgkmcnt(3)
	v_mfma_f32_16x16x32_bf16 v[116:119], v[144:147], v[200:203], v[116:119]
	v_mfma_f32_16x16x32_bf16 v[124:127], v[148:151], v[200:203], v[124:127]
	ds_read_b128 v[200:203], v246 offset:13312
	s_waitcnt lgkmcnt(3)
	v_mfma_f32_16x16x32_bf16 v[96:99], v[144:147], v[204:207], v[96:99]
	v_mfma_f32_16x16x32_bf16 v[104:107], v[148:151], v[204:207], v[104:107]
	ds_read_b128 v[204:207], v246 offset:14336
	s_waitcnt lgkmcnt(3)
	v_mfma_f32_16x16x32_bf16 v[100:103], v[144:147], v[242:245], v[100:103]
	v_mfma_f32_16x16x32_bf16 v[108:111], v[148:151], v[242:245], v[108:111]
	ds_read_b128 v[242:245], v246 offset:15360
	s_waitcnt lgkmcnt(3)
	v_mfma_f32_16x16x32_bf16 v[80:83], v[144:147], v[196:199], v[80:83]
	v_mfma_f32_16x16x32_bf16 v[88:91], v[148:151], v[196:199], v[88:91]
	s_waitcnt lgkmcnt(2)
	v_mfma_f32_16x16x32_bf16 v[84:87], v[144:147], v[200:203], v[84:87]
	v_mfma_f32_16x16x32_bf16 v[92:95], v[148:151], v[200:203], v[92:95]
	s_waitcnt lgkmcnt(1)
	v_mfma_f32_16x16x32_bf16 v[64:67], v[144:147], v[204:207], v[64:67]
	v_mfma_f32_16x16x32_bf16 v[72:75], v[148:151], v[204:207], v[72:75]
	s_waitcnt lgkmcnt(0)
	v_mfma_f32_16x16x32_bf16 v[68:71], v[144:147], v[242:245], v[68:71]
	v_mfma_f32_16x16x32_bf16 v[76:79], v[148:151], v[242:245], v[76:79]
	global_load_dwordx4 v[144:147], v[248:249], off
	global_load_dwordx4 v[148:151], v[248:249], off offset:256
	s_waitcnt vmcnt(6)
	s_barrier
	ds_read_b128 v[196:199], v246 offset:16384
	ds_read_b128 v[200:203], v246 offset:17408
	ds_read_b128 v[204:207], v246 offset:18432
	ds_read_b128 v[242:245], v246 offset:19456
	s_waitcnt vmcnt(4) lgkmcnt(3)
	v_mfma_f32_16x16x32_bf16 v[112:115], v[128:131], v[196:199], v[112:115]
	v_mfma_f32_16x16x32_bf16 v[120:123], v[132:135], v[196:199], v[120:123]
	ds_read_b128 v[196:199], v246 offset:20480
	s_waitcnt lgkmcnt(3)
	v_mfma_f32_16x16x32_bf16 v[116:119], v[128:131], v[200:203], v[116:119]
	v_mfma_f32_16x16x32_bf16 v[124:127], v[132:135], v[200:203], v[124:127]
	ds_read_b128 v[200:203], v246 offset:21504
	s_waitcnt lgkmcnt(3)
	v_mfma_f32_16x16x32_bf16 v[96:99], v[128:131], v[204:207], v[96:99]
	v_mfma_f32_16x16x32_bf16 v[104:107], v[132:135], v[204:207], v[104:107]
	ds_read_b128 v[204:207], v246 offset:22528
	s_waitcnt lgkmcnt(3)
	v_mfma_f32_16x16x32_bf16 v[100:103], v[128:131], v[242:245], v[100:103]
	v_mfma_f32_16x16x32_bf16 v[108:111], v[132:135], v[242:245], v[108:111]
	ds_read_b128 v[242:245], v246 offset:23552
	s_waitcnt lgkmcnt(3)
	v_mfma_f32_16x16x32_bf16 v[80:83], v[128:131], v[196:199], v[80:83]
	v_mfma_f32_16x16x32_bf16 v[88:91], v[132:135], v[196:199], v[88:91]
	s_waitcnt lgkmcnt(2)
	v_mfma_f32_16x16x32_bf16 v[84:87], v[128:131], v[200:203], v[84:87]
	v_mfma_f32_16x16x32_bf16 v[92:95], v[132:135], v[200:203], v[92:95]
	s_waitcnt lgkmcnt(1)
	v_mfma_f32_16x16x32_bf16 v[64:67], v[128:131], v[204:207], v[64:67]
	v_mfma_f32_16x16x32_bf16 v[72:75], v[132:135], v[204:207], v[72:75]
	s_waitcnt lgkmcnt(0)
	v_mfma_f32_16x16x32_bf16 v[68:71], v[128:131], v[242:245], v[68:71]
	v_mfma_f32_16x16x32_bf16 v[76:79], v[132:135], v[242:245], v[76:79]
	s_waitcnt vmcnt(2)
	s_barrier
	ds_read_b128 v[196:199], v246 offset:0
	ds_read_b128 v[200:203], v246 offset:1024
	ds_read_b128 v[204:207], v246 offset:2048
	ds_read_b128 v[242:245], v246 offset:3072
	s_waitcnt vmcnt(0) lgkmcnt(3)
	v_mfma_f32_16x16x32_bf16 v[112:115], v[144:147], v[196:199], v[112:115]
	v_mfma_f32_16x16x32_bf16 v[120:123], v[148:151], v[196:199], v[120:123]
	ds_read_b128 v[196:199], v246 offset:4096
	s_waitcnt lgkmcnt(3)
	v_mfma_f32_16x16x32_bf16 v[116:119], v[144:147], v[200:203], v[116:119]
	v_mfma_f32_16x16x32_bf16 v[124:127], v[148:151], v[200:203], v[124:127]
	ds_read_b128 v[200:203], v246 offset:5120
	s_waitcnt lgkmcnt(3)
	v_mfma_f32_16x16x32_bf16 v[96:99], v[144:147], v[204:207], v[96:99]
	v_mfma_f32_16x16x32_bf16 v[104:107], v[148:151], v[204:207], v[104:107]
	ds_read_b128 v[204:207], v246 offset:6144
	s_waitcnt lgkmcnt(3)
	v_mfma_f32_16x16x32_bf16 v[100:103], v[144:147], v[242:245], v[100:103]
	v_mfma_f32_16x16x32_bf16 v[108:111], v[148:151], v[242:245], v[108:111]
	ds_read_b128 v[242:245], v246 offset:7168
	v_permlane16_swap_b32_e32 v112, v116
	v_permlane16_swap_b32_e32 v113, v117
	v_permlane16_swap_b32_e32 v114, v118
	v_permlane16_swap_b32_e32 v115, v119
	v_permlane16_swap_b32_e32 v120, v124
	v_permlane16_swap_b32_e32 v121, v125
	v_permlane16_swap_b32_e32 v122, v126
	v_permlane16_swap_b32_e32 v123, v127
	v_permlane16_swap_b32_e32 v48, v52
	v_permlane16_swap_b32_e32 v49, v53
	v_permlane16_swap_b32_e32 v50, v54
	v_permlane16_swap_b32_e32 v51, v55
	v_permlane16_swap_b32_e32 v56, v60
	v_permlane16_swap_b32_e32 v57, v61
	v_permlane16_swap_b32_e32 v58, v62
	v_permlane16_swap_b32_e32 v59, v63
	v_permlane32_swap_b32_e32 v112, v116
	v_permlane32_swap_b32_e32 v113, v117
	v_permlane32_swap_b32_e32 v114, v118
	v_permlane32_swap_b32_e32 v115, v119
	v_permlane32_swap_b32_e32 v120, v124
	v_permlane32_swap_b32_e32 v121, v125
	v_permlane32_swap_b32_e32 v122, v126
	v_permlane32_swap_b32_e32 v123, v127
	v_permlane32_swap_b32_e32 v48, v52
	v_permlane32_swap_b32_e32 v49, v53
	v_permlane32_swap_b32_e32 v50, v54
	v_permlane32_swap_b32_e32 v51, v55
	v_permlane32_swap_b32_e32 v56, v60
	v_permlane32_swap_b32_e32 v57, v61
	v_permlane32_swap_b32_e32 v58, v62
	v_permlane32_swap_b32_e32 v59, v63
	s_waitcnt lgkmcnt(3)
	v_mfma_f32_16x16x32_bf16 v[80:83], v[144:147], v[196:199], v[80:83]
	v_mfma_f32_16x16x32_bf16 v[88:91], v[148:151], v[196:199], v[88:91]
	s_waitcnt lgkmcnt(2)
	v_mfma_f32_16x16x32_bf16 v[84:87], v[144:147], v[200:203], v[84:87]
	v_mfma_f32_16x16x32_bf16 v[92:95], v[148:151], v[200:203], v[92:95]
	v_permlane16_swap_b32_e32 v96, v100
	v_permlane16_swap_b32_e32 v97, v101
	v_permlane16_swap_b32_e32 v98, v102
	v_permlane16_swap_b32_e32 v99, v103
	v_permlane16_swap_b32_e32 v104, v108
	v_permlane16_swap_b32_e32 v105, v109
	v_permlane16_swap_b32_e32 v106, v110
	v_permlane16_swap_b32_e32 v107, v111
	v_permlane16_swap_b32_e32 v32, v36
	v_permlane16_swap_b32_e32 v33, v37
	v_permlane16_swap_b32_e32 v34, v38
	v_permlane16_swap_b32_e32 v35, v39
	v_permlane16_swap_b32_e32 v40, v44
	v_permlane16_swap_b32_e32 v41, v45
	v_permlane16_swap_b32_e32 v42, v46
	v_permlane16_swap_b32_e32 v43, v47
	v_permlane32_swap_b32_e32 v96, v100
	v_permlane32_swap_b32_e32 v97, v101
	v_permlane32_swap_b32_e32 v98, v102
	v_permlane32_swap_b32_e32 v99, v103
	v_permlane32_swap_b32_e32 v104, v108
	v_permlane32_swap_b32_e32 v105, v109
	v_permlane32_swap_b32_e32 v106, v110
	v_permlane32_swap_b32_e32 v107, v111
	v_permlane32_swap_b32_e32 v32, v36
	v_permlane32_swap_b32_e32 v33, v37
	v_permlane32_swap_b32_e32 v34, v38
	v_permlane32_swap_b32_e32 v35, v39
	v_permlane32_swap_b32_e32 v40, v44
	v_permlane32_swap_b32_e32 v41, v45
	v_permlane32_swap_b32_e32 v42, v46
	v_permlane32_swap_b32_e32 v43, v47
	s_waitcnt lgkmcnt(1)
	v_mfma_f32_16x16x32_bf16 v[64:67], v[144:147], v[204:207], v[64:67]
	v_mfma_f32_16x16x32_bf16 v[72:75], v[148:151], v[204:207], v[72:75]
	s_waitcnt lgkmcnt(0)
	v_mfma_f32_16x16x32_bf16 v[68:71], v[144:147], v[242:245], v[68:71]
	v_mfma_f32_16x16x32_bf16 v[76:79], v[148:151], v[242:245], v[76:79]
	v_permlane16_swap_b32_e32 v80, v84
	v_permlane16_swap_b32_e32 v81, v85
	v_permlane16_swap_b32_e32 v82, v86
	v_permlane16_swap_b32_e32 v83, v87
	v_permlane16_swap_b32_e32 v88, v92
	v_permlane16_swap_b32_e32 v89, v93
	v_permlane16_swap_b32_e32 v90, v94
	v_permlane16_swap_b32_e32 v91, v95
	v_permlane16_swap_b32_e32 v16, v20
	v_permlane16_swap_b32_e32 v17, v21
	v_permlane16_swap_b32_e32 v18, v22
	v_permlane16_swap_b32_e32 v19, v23
	v_permlane16_swap_b32_e32 v24, v28
	v_permlane16_swap_b32_e32 v25, v29
	v_permlane16_swap_b32_e32 v26, v30
	v_permlane16_swap_b32_e32 v27, v31
	v_permlane32_swap_b32_e32 v80, v84
	v_permlane32_swap_b32_e32 v81, v85
	v_permlane32_swap_b32_e32 v82, v86
	v_permlane32_swap_b32_e32 v83, v87
	v_permlane32_swap_b32_e32 v88, v92
	v_permlane32_swap_b32_e32 v89, v93
	v_permlane32_swap_b32_e32 v90, v94
	v_permlane32_swap_b32_e32 v91, v95
	v_permlane32_swap_b32_e32 v16, v20
	v_permlane32_swap_b32_e32 v17, v21
	v_permlane32_swap_b32_e32 v18, v22
	v_permlane32_swap_b32_e32 v19, v23
	v_permlane32_swap_b32_e32 v24, v28
	v_permlane32_swap_b32_e32 v25, v29
	v_permlane32_swap_b32_e32 v26, v30
	v_permlane32_swap_b32_e32 v27, v31
	s_barrier
	s_nop 7
	v_permlane16_swap_b32_e32 v64, v68
	v_permlane16_swap_b32_e32 v65, v69
	v_permlane16_swap_b32_e32 v66, v70
	v_permlane16_swap_b32_e32 v67, v71
	v_permlane16_swap_b32_e32 v72, v76
	v_permlane16_swap_b32_e32 v73, v77
	v_permlane16_swap_b32_e32 v74, v78
	v_permlane16_swap_b32_e32 v75, v79
	v_permlane16_swap_b32_e32 v0, v4
	v_permlane16_swap_b32_e32 v1, v5
	v_permlane16_swap_b32_e32 v2, v6
	v_permlane16_swap_b32_e32 v3, v7
	v_permlane16_swap_b32_e32 v8, v12
	v_permlane16_swap_b32_e32 v9, v13
	v_permlane16_swap_b32_e32 v10, v14
	v_permlane16_swap_b32_e32 v11, v15
	v_permlane32_swap_b32_e32 v64, v68
	v_permlane32_swap_b32_e32 v65, v69
	v_permlane32_swap_b32_e32 v66, v70
	v_permlane32_swap_b32_e32 v67, v71
	v_permlane32_swap_b32_e32 v72, v76
	v_permlane32_swap_b32_e32 v73, v77
	v_permlane32_swap_b32_e32 v74, v78
	v_permlane32_swap_b32_e32 v75, v79
	v_permlane32_swap_b32_e32 v0, v4
	v_permlane32_swap_b32_e32 v1, v5
	v_permlane32_swap_b32_e32 v2, v6
	v_permlane32_swap_b32_e32 v3, v7
	v_permlane32_swap_b32_e32 v8, v12
	v_permlane32_swap_b32_e32 v9, v13
	v_permlane32_swap_b32_e32 v10, v14
	v_permlane32_swap_b32_e32 v11, v15
	s_waitcnt vmcnt(0)
	s_waitcnt vmcnt(0)
	v_and_b32_e32 v188, 63, v179
	v_lshrrev_b32_e32 v189, 6, v179
	v_mul_u32_u24_e32 v249, 0x2400, v189
	v_mov_b32_e32 v250, v249
	v_lshrrev_b32_e32 v251, 5, v188
	v_mul_u32_u24_e32 v251, 0x440, v251
	v_add_u32_e32 v249, v249, v251
	v_and_b32_e32 v251, 31, v188
	v_lshl_add_u32 v249, v251, 2, v249
	v_lshrrev_b32_e32 v237, 4, v188
	v_mul_u32_u24_e32 v251, 0x110, v237
	v_add_u32_e32 v250, v250, v251
	v_and_b32_e32 v251, 15, v188
	v_lshlrev_b32_e32 v251, 4, v251
	v_add_u32_e32 v250, v250, v251
	v_lshl_add_u32 v237, v189, 6, v237
	v_lshl_add_u32 v237, v237, 12, v251
	v_add_u32_e32 v238, 16384, v237
	v_add_u32_e32 v239, 32768, v237
	v_add_u32_e32 v240, 49152, v237
	v_add_u32_e32 v241, 65536, v237
	v_add_u32_e32 v242, 81920, v237
	v_add_u32_e32 v243, 98304, v237
	v_add_u32_e32 v248, 114688, v237
	s_lshl_b32 s16, s7, 8
	s_lshl_b32 s18, s6, 9
	s_lshr_b32 s19, s7, 4
	v_readlane_b32 s12, v253, 46
	v_readlane_b32 s13, v253, 47
	v_readlane_b32 s14, v253, 46
	v_readlane_b32 s15, v253, 47
	s_add_i32 s17, s16, 0xffff8000
	s_cmpk_lt_u32 s7, 0x80
	s_cselect_b32 s12, s12, s62
	s_cselect_b32 s13, s13, s63
	s_cselect_b32 s14, s14, s62
	s_cselect_b32 s15, s15, s63
	s_cselect_b32 s19, s19, 8
	s_cselect_b32 s16, s16, s17
	s_mov_b32 s17, 0
	s_lshl_b64 s[16:17], s[16:17], 12
	s_add_u32 s16, s16, s18
	s_addc_u32 s17, s17, 0
	s_add_u32 s12, s12, s16
	s_addc_u32 s13, s13, s17
	s_add_u32 s14, s14, s16
	s_addc_u32 s15, s15, s17
	s_mul_i32 s19, s19, 0x6000
	s_add_u32 s20, s0, s19
	s_addc_u32 s21, s1, 0
	s_add_u32 s20, s20, s18
	s_addc_u32 s21, s21, 0
	s_cmp_eq_u32 s101, 1
	s_cbranch_scc0 .Lre_downh_h0
	s_add_u32 s12, s12, 0x20000
	s_addc_u32 s13, s13, 0
	s_add_u32 s14, s14, 0x20000
	s_addc_u32 s15, s15, 0
.Lre_downh_h0:
	global_load_dwordx4 v[244:247], v251, s[20:21]
	global_load_dwordx4 v[160:163], v237, s[12:13]
	global_load_dwordx4 v[164:167], v238, s[12:13]
	global_load_dwordx4 v[168:171], v239, s[12:13]
	global_load_dwordx4 v[172:175], v240, s[12:13]
	global_load_dwordx4 v[196:199], v241, s[12:13]
	global_load_dwordx4 v[200:203], v242, s[12:13]
	global_load_dwordx4 v[204:207], v243, s[12:13]
	global_load_dwordx4 v[184:187], v248, s[12:13]
	ds_write_b32 v249, v112
	ds_write_b32 v249, v113 offset:272
	ds_write_b32 v249, v114 offset:544
	ds_write_b32 v249, v115 offset:816
	ds_write_b32 v249, v116 offset:2176
	ds_write_b32 v249, v117 offset:2448
	ds_write_b32 v249, v118 offset:2720
	ds_write_b32 v249, v119 offset:2992
	ds_write_b32 v249, v120 offset:4352
	ds_write_b32 v249, v121 offset:4624
	ds_write_b32 v249, v122 offset:4896
	ds_write_b32 v249, v123 offset:5168
	ds_write_b32 v249, v124 offset:6528
	ds_write_b32 v249, v125 offset:6800
	ds_write_b32 v249, v126 offset:7072
	ds_write_b32 v249, v127 offset:7344
	ds_write_b32 v249, v96 offset:128
	ds_write_b32 v249, v97 offset:400
	ds_write_b32 v249, v98 offset:672
	ds_write_b32 v249, v99 offset:944
	ds_write_b32 v249, v100 offset:2304
	ds_write_b32 v249, v101 offset:2576
	ds_write_b32 v249, v102 offset:2848
	ds_write_b32 v249, v103 offset:3120
	ds_write_b32 v249, v104 offset:4480
	ds_write_b32 v249, v105 offset:4752
	ds_write_b32 v249, v106 offset:5024
	ds_write_b32 v249, v107 offset:5296
	ds_write_b32 v249, v108 offset:6656
	ds_write_b32 v249, v109 offset:6928
	ds_write_b32 v249, v110 offset:7200
	ds_write_b32 v249, v111 offset:7472
	s_waitcnt lgkmcnt(0)
	ds_read_b128 v[128:131], v250
	ds_read_b128 v[132:135], v250 offset:1088
	ds_read_b128 v[136:139], v250 offset:2176
	ds_read_b128 v[140:143], v250 offset:3264
	ds_read_b128 v[144:147], v250 offset:4352
	ds_read_b128 v[148:151], v250 offset:5440
	ds_read_b128 v[152:155], v250 offset:6528
	ds_read_b128 v[156:159], v250 offset:7616
	s_waitcnt vmcnt(7) lgkmcnt(7)
	v_fma_f32 v128, v244, v128, v160
	v_fma_f32 v129, v245, v129, v161
	v_fma_f32 v130, v246, v130, v162
	v_fma_f32 v131, v247, v131, v163
	global_store_dwordx4 v237, v[128:131], s[14:15]
	s_waitcnt vmcnt(7) lgkmcnt(6)
	v_fma_f32 v132, v244, v132, v164
	v_fma_f32 v133, v245, v133, v165
	v_fma_f32 v134, v246, v134, v166
	v_fma_f32 v135, v247, v135, v167
	global_store_dwordx4 v238, v[132:135], s[14:15]
	s_waitcnt vmcnt(7) lgkmcnt(5)
	v_fma_f32 v136, v244, v136, v168
	v_fma_f32 v137, v245, v137, v169
	v_fma_f32 v138, v246, v138, v170
	v_fma_f32 v139, v247, v139, v171
	global_store_dwordx4 v239, v[136:139], s[14:15]
	s_waitcnt vmcnt(7) lgkmcnt(4)
	v_fma_f32 v140, v244, v140, v172
	v_fma_f32 v141, v245, v141, v173
	v_fma_f32 v142, v246, v142, v174
	v_fma_f32 v143, v247, v143, v175
	global_store_dwordx4 v240, v[140:143], s[14:15]
	s_waitcnt vmcnt(7) lgkmcnt(3)
	v_fma_f32 v144, v244, v144, v196
	v_fma_f32 v145, v245, v145, v197
	v_fma_f32 v146, v246, v146, v198
	v_fma_f32 v147, v247, v147, v199
	global_store_dwordx4 v241, v[144:147], s[14:15]
	s_waitcnt vmcnt(7) lgkmcnt(2)
	v_fma_f32 v148, v244, v148, v200
	v_fma_f32 v149, v245, v149, v201
	v_fma_f32 v150, v246, v150, v202
	v_fma_f32 v151, v247, v151, v203
	global_store_dwordx4 v242, v[148:151], s[14:15]
	s_waitcnt vmcnt(7) lgkmcnt(1)
	v_fma_f32 v152, v244, v152, v204
	v_fma_f32 v153, v245, v153, v205
	v_fma_f32 v154, v246, v154, v206
	v_fma_f32 v155, v247, v155, v207
	global_store_dwordx4 v243, v[152:155], s[14:15]
	s_waitcnt vmcnt(7) lgkmcnt(0)
	v_fma_f32 v156, v244, v156, v184
	v_fma_f32 v157, v245, v157, v185
	v_fma_f32 v158, v246, v158, v186
	v_fma_f32 v159, v247, v159, v187
	global_store_dwordx4 v248, v[156:159], s[14:15]
	global_load_dwordx4 v[244:247], v251, s[20:21] offset:256
	global_load_dwordx4 v[160:163], v237, s[12:13] offset:256
	global_load_dwordx4 v[164:167], v238, s[12:13] offset:256
	global_load_dwordx4 v[168:171], v239, s[12:13] offset:256
	global_load_dwordx4 v[172:175], v240, s[12:13] offset:256
	global_load_dwordx4 v[196:199], v241, s[12:13] offset:256
	global_load_dwordx4 v[200:203], v242, s[12:13] offset:256
	global_load_dwordx4 v[204:207], v243, s[12:13] offset:256
	global_load_dwordx4 v[184:187], v248, s[12:13] offset:256
	ds_write_b32 v249, v80
	ds_write_b32 v249, v81 offset:272
	ds_write_b32 v249, v82 offset:544
	ds_write_b32 v249, v83 offset:816
	ds_write_b32 v249, v84 offset:2176
	ds_write_b32 v249, v85 offset:2448
	ds_write_b32 v249, v86 offset:2720
	ds_write_b32 v249, v87 offset:2992
	ds_write_b32 v249, v88 offset:4352
	ds_write_b32 v249, v89 offset:4624
	ds_write_b32 v249, v90 offset:4896
	ds_write_b32 v249, v91 offset:5168
	ds_write_b32 v249, v92 offset:6528
	ds_write_b32 v249, v93 offset:6800
	ds_write_b32 v249, v94 offset:7072
	ds_write_b32 v249, v95 offset:7344
	ds_write_b32 v249, v64 offset:128
	ds_write_b32 v249, v65 offset:400
	ds_write_b32 v249, v66 offset:672
	ds_write_b32 v249, v67 offset:944
	ds_write_b32 v249, v68 offset:2304
	ds_write_b32 v249, v69 offset:2576
	ds_write_b32 v249, v70 offset:2848
	ds_write_b32 v249, v71 offset:3120
	ds_write_b32 v249, v72 offset:4480
	ds_write_b32 v249, v73 offset:4752
	ds_write_b32 v249, v74 offset:5024
	ds_write_b32 v249, v75 offset:5296
	ds_write_b32 v249, v76 offset:6656
	ds_write_b32 v249, v77 offset:6928
	ds_write_b32 v249, v78 offset:7200
	ds_write_b32 v249, v79 offset:7472
	s_waitcnt lgkmcnt(0)
	ds_read_b128 v[128:131], v250
	ds_read_b128 v[132:135], v250 offset:1088
	ds_read_b128 v[136:139], v250 offset:2176
	ds_read_b128 v[140:143], v250 offset:3264
	ds_read_b128 v[144:147], v250 offset:4352
	ds_read_b128 v[148:151], v250 offset:5440
	ds_read_b128 v[152:155], v250 offset:6528
	ds_read_b128 v[156:159], v250 offset:7616
	s_waitcnt vmcnt(7) lgkmcnt(7)
	v_fma_f32 v128, v244, v128, v160
	v_fma_f32 v129, v245, v129, v161
	v_fma_f32 v130, v246, v130, v162
	v_fma_f32 v131, v247, v131, v163
	global_store_dwordx4 v237, v[128:131], s[14:15] offset:256
	s_waitcnt vmcnt(7) lgkmcnt(6)
	v_fma_f32 v132, v244, v132, v164
	v_fma_f32 v133, v245, v133, v165
	v_fma_f32 v134, v246, v134, v166
	v_fma_f32 v135, v247, v135, v167
	global_store_dwordx4 v238, v[132:135], s[14:15] offset:256
	s_waitcnt vmcnt(7) lgkmcnt(5)
	v_fma_f32 v136, v244, v136, v168
	v_fma_f32 v137, v245, v137, v169
	v_fma_f32 v138, v246, v138, v170
	v_fma_f32 v139, v247, v139, v171
	global_store_dwordx4 v239, v[136:139], s[14:15] offset:256
	s_waitcnt vmcnt(7) lgkmcnt(4)
	v_fma_f32 v140, v244, v140, v172
	v_fma_f32 v141, v245, v141, v173
	v_fma_f32 v142, v246, v142, v174
	v_fma_f32 v143, v247, v143, v175
	global_store_dwordx4 v240, v[140:143], s[14:15] offset:256
	s_waitcnt vmcnt(7) lgkmcnt(3)
	v_fma_f32 v144, v244, v144, v196
	v_fma_f32 v145, v245, v145, v197
	v_fma_f32 v146, v246, v146, v198
	v_fma_f32 v147, v247, v147, v199
	global_store_dwordx4 v241, v[144:147], s[14:15] offset:256
	s_waitcnt vmcnt(7) lgkmcnt(2)
	v_fma_f32 v148, v244, v148, v200
	v_fma_f32 v149, v245, v149, v201
	v_fma_f32 v150, v246, v150, v202
	v_fma_f32 v151, v247, v151, v203
	global_store_dwordx4 v242, v[148:151], s[14:15] offset:256
	s_waitcnt vmcnt(7) lgkmcnt(1)
	v_fma_f32 v152, v244, v152, v204
	v_fma_f32 v153, v245, v153, v205
	v_fma_f32 v154, v246, v154, v206
	v_fma_f32 v155, v247, v155, v207
	global_store_dwordx4 v243, v[152:155], s[14:15] offset:256
	s_waitcnt vmcnt(7) lgkmcnt(0)
	v_fma_f32 v156, v244, v156, v184
	v_fma_f32 v157, v245, v157, v185
	v_fma_f32 v158, v246, v158, v186
	v_fma_f32 v159, v247, v159, v187
	global_store_dwordx4 v248, v[156:159], s[14:15] offset:256
	s_waitcnt lgkmcnt(0)
	s_mov_b32 s100, 0
	s_barrier
	s_branch .LBB0_1089
